# P4 epilogue conv: lane shifts folded into DPP multiply-adds (6 slots per element instead of 10)
# speedup vs baseline: 1.0276x; 1.0069x over previous
;     __device__ __forceinline__ void operator()(f32x4 (&acc)[2][2][4][2], const Unit& u, int wr, int wc, int fr_, int fq_) const {
;     ...
;                     for (int m = 0; m < 4; ++m) { const f32x4 cur = acc[ai][bj][m][n]; f32x4 o;
; #pragma unroll
;                         for (int i = 0; i < 4; ++i) {
;                             float s1, s2;
;                             asm volatile("s_nop 1\n\tv_mov_b32_dpp %0, %2 row_ror:1 row_mask:0xf bank_mask:0xf\n\tv_mov_b32_dpp %1, %2 row_ror:2 row_mask:0xf bank_mask:0xf\n\t"
;                                          "v_mov_b32_dpp %0, %3 row_shr:1 row_mask:0xf bank_mask:0xf\n\tv_mov_b32_dpp %1, %3 row_shr:2 row_mask:0xf bank_mask:0xf"
;                                          : "=&v"(s1), "=&v"(s2) : "v"(prev[i]), "v"(cur[i]), "v"(w1[i]), "v"(w0[i]));
;                             float t = bb[i] + w2[i] * cur[i] + w1[i] * s1 + w0[i] * s2; asm volatile("" : "+v"(t)); o[i] = t; }
;                         acc[ai][bj][m][n] = o; prev = cur; __builtin_amdgcn_sched_barrier(0); }
.LBB0_670:
	v_or_b32_e32 v195, 16, v176
	s_waitcnt vmcnt(4)
	v_fma_f32 v227, v160, v150, v90
	v_pk_mul_f32 v[228:229], v[116:117], v[194:195] op_sel_hi:[1,0]
	v_pk_mul_f32 v[116:117], v[114:115], v[194:195] op_sel_hi:[1,0]
	s_waitcnt lgkmcnt(0)
	v_mul_f32_dpp v114, v164, v146 row_shl:15 row_mask:0xf bank_mask:0xf bound_ctrl:0
	v_fmac_f32_dpp v114, v164, v142 row_shl:14 row_mask:0xf bank_mask:0xf
	v_fmac_f32_dpp v114, v160, v146 row_shr:1 row_mask:0xf bank_mask:0xf
	v_fmac_f32_dpp v114, v160, v142 row_shr:2 row_mask:0xf bank_mask:0xf
	v_fma_f32 v235, v163, v153, v93
	v_add_f32_e32 v227, v227, v114
	v_mul_f32_dpp v114, v165, v147 row_shl:15 row_mask:0xf bank_mask:0xf bound_ctrl:0
	v_fmac_f32_dpp v114, v165, v143 row_shl:14 row_mask:0xf bank_mask:0xf
	v_fmac_f32_dpp v114, v161, v147 row_shr:1 row_mask:0xf bank_mask:0xf
	v_fmac_f32_dpp v114, v161, v143 row_shr:2 row_mask:0xf bank_mask:0xf
	v_fma_f32 v165, v161, v151, v91
	v_add_f32_e32 v165, v165, v114
	v_mul_f32_dpp v114, v166, v148 row_shl:15 row_mask:0xf bank_mask:0xf bound_ctrl:0
	v_fmac_f32_dpp v114, v166, v144 row_shl:14 row_mask:0xf bank_mask:0xf
	v_fmac_f32_dpp v114, v162, v148 row_shr:1 row_mask:0xf bank_mask:0xf
	v_fmac_f32_dpp v114, v162, v144 row_shr:2 row_mask:0xf bank_mask:0xf
	v_fma_f32 v166, v162, v152, v92
	v_add_f32_e32 v166, v166, v114
	v_mul_f32_dpp v114, v167, v149 row_shl:15 row_mask:0xf bank_mask:0xf bound_ctrl:0
	v_fmac_f32_dpp v114, v167, v145 row_shl:14 row_mask:0xf bank_mask:0xf
	v_fmac_f32_dpp v114, v163, v149 row_shr:1 row_mask:0xf bank_mask:0xf
	v_fmac_f32_dpp v114, v163, v145 row_shr:2 row_mask:0xf bank_mask:0xf
	v_pk_mul_f32 v[108:109], v[108:109], v[192:193] op_sel_hi:[1,0]
	v_add_f32_e32 v235, v235, v114
	v_pk_mul_f32 v[106:107], v[106:107], v[192:193] op_sel_hi:[1,0]
	v_pk_mul_f32 v[104:105], v[104:105], v[200:201] op_sel_hi:[1,0]
	v_pk_mul_f32 v[102:103], v[102:103], v[200:201] op_sel_hi:[1,0]
	v_pk_mul_f32 v[96:97], v[96:97], v[198:199] op_sel_hi:[1,0]
	v_pk_mul_f32 v[94:95], v[94:95], v[198:199] op_sel_hi:[1,0]
	v_pk_mul_f32 v[52:53], v[52:53], v[196:197] op_sel_hi:[1,0]
	v_pk_mul_f32 v[50:51], v[50:51], v[196:197] op_sel_hi:[1,0]
	v_lshl_add_u64 v[204:205], s[86:87], 0, v[176:177]
	v_lshl_add_u64 v[202:203], s[88:89], 0, v[176:177]
	v_fma_f32 v114, v116, v150, v90
	v_mul_f32_dpp v115, v160, v146 row_shl:15 row_mask:0xf bank_mask:0xf bound_ctrl:0
	v_fmac_f32_dpp v115, v160, v142 row_shl:14 row_mask:0xf bank_mask:0xf
	v_fmac_f32_dpp v115, v116, v146 row_shr:1 row_mask:0xf bank_mask:0xf
	v_fmac_f32_dpp v115, v116, v142 row_shr:2 row_mask:0xf bank_mask:0xf
	v_fma_f32 v167, v229, v153, v93
	v_add_f32_e32 v114, v114, v115
	v_fma_f32 v115, v117, v151, v91
	v_mul_f32_dpp v160, v161, v147 row_shl:15 row_mask:0xf bank_mask:0xf bound_ctrl:0
	v_fmac_f32_dpp v160, v161, v143 row_shl:14 row_mask:0xf bank_mask:0xf
	v_fmac_f32_dpp v160, v117, v147 row_shr:1 row_mask:0xf bank_mask:0xf
	v_fmac_f32_dpp v160, v117, v143 row_shr:2 row_mask:0xf bank_mask:0xf
	s_nop 0
	v_add_f32_e32 v115, v115, v160
	v_mul_f32_dpp v160, v162, v148 row_shl:15 row_mask:0xf bank_mask:0xf bound_ctrl:0
	v_fmac_f32_dpp v160, v162, v144 row_shl:14 row_mask:0xf bank_mask:0xf
	v_fmac_f32_dpp v160, v228, v148 row_shr:1 row_mask:0xf bank_mask:0xf
	v_fmac_f32_dpp v160, v228, v144 row_shr:2 row_mask:0xf bank_mask:0xf
	v_fma_f32 v162, v228, v152, v92
	v_add_f32_e32 v162, v162, v160
	v_mul_f32_dpp v160, v163, v149 row_shl:15 row_mask:0xf bank_mask:0xf bound_ctrl:0
	v_fmac_f32_dpp v160, v163, v145 row_shl:14 row_mask:0xf bank_mask:0xf
	v_fmac_f32_dpp v160, v229, v149 row_shr:1 row_mask:0xf bank_mask:0xf
	v_fmac_f32_dpp v160, v229, v145 row_shr:2 row_mask:0xf bank_mask:0xf
	s_nop 0
	v_add_f32_e32 v167, v167, v160
	v_mul_f32_dpp v160, v116, v146 row_shl:15 row_mask:0xf bank_mask:0xf bound_ctrl:0
	v_fmac_f32_dpp v160, v116, v142 row_shl:14 row_mask:0xf bank_mask:0xf
	v_fmac_f32_dpp v160, v106, v146 row_shr:1 row_mask:0xf bank_mask:0xf
	v_fmac_f32_dpp v160, v106, v142 row_shr:2 row_mask:0xf bank_mask:0xf
	v_fma_f32 v116, v106, v150, v90
	v_add_f32_e32 v116, v116, v160
	v_mul_f32_dpp v160, v117, v147 row_shl:15 row_mask:0xf bank_mask:0xf bound_ctrl:0
	v_fmac_f32_dpp v160, v117, v143 row_shl:14 row_mask:0xf bank_mask:0xf
	v_fmac_f32_dpp v160, v107, v147 row_shr:1 row_mask:0xf bank_mask:0xf
	v_fmac_f32_dpp v160, v107, v143 row_shr:2 row_mask:0xf bank_mask:0xf
	v_fma_f32 v117, v107, v151, v91
	v_add_f32_e32 v117, v117, v160
	v_fma_f32 v163, v108, v152, v92
	v_mul_f32_dpp v160, v228, v148 row_shl:15 row_mask:0xf bank_mask:0xf bound_ctrl:0
	v_fmac_f32_dpp v160, v228, v144 row_shl:14 row_mask:0xf bank_mask:0xf
	v_fmac_f32_dpp v160, v108, v148 row_shr:1 row_mask:0xf bank_mask:0xf
	v_fmac_f32_dpp v160, v108, v144 row_shr:2 row_mask:0xf bank_mask:0xf
	v_fma_f32 v228, v109, v153, v93
	v_add_f32_e32 v163, v163, v160
	v_mul_f32_dpp v160, v229, v149 row_shl:15 row_mask:0xf bank_mask:0xf bound_ctrl:0
	v_fmac_f32_dpp v160, v229, v145 row_shl:14 row_mask:0xf bank_mask:0xf
	v_fmac_f32_dpp v160, v109, v149 row_shr:1 row_mask:0xf bank_mask:0xf
	v_fmac_f32_dpp v160, v109, v145 row_shr:2 row_mask:0xf bank_mask:0xf
	s_nop 0
	v_add_f32_e32 v228, v228, v160
	v_fma_f32 v160, v156, v150, v90
	v_mul_f32_dpp v161, v106, v146 row_shl:15 row_mask:0xf bank_mask:0xf bound_ctrl:0
	v_fmac_f32_dpp v161, v106, v142 row_shl:14 row_mask:0xf bank_mask:0xf
	v_fmac_f32_dpp v161, v156, v146 row_shr:1 row_mask:0xf bank_mask:0xf
	v_fmac_f32_dpp v161, v156, v142 row_shr:2 row_mask:0xf bank_mask:0xf
	v_fma_f32 v231, v159, v153, v93
	v_add_f32_e32 v160, v160, v161
	v_fma_f32 v161, v157, v151, v91
	v_mul_f32_dpp v106, v107, v147 row_shl:15 row_mask:0xf bank_mask:0xf bound_ctrl:0
	v_fmac_f32_dpp v106, v107, v143 row_shl:14 row_mask:0xf bank_mask:0xf
	v_fmac_f32_dpp v106, v157, v147 row_shr:1 row_mask:0xf bank_mask:0xf
	v_fmac_f32_dpp v106, v157, v143 row_shr:2 row_mask:0xf bank_mask:0xf
	v_fma_f32 v164, v158, v152, v92
	v_add_f32_e32 v161, v161, v106
	v_mul_f32_dpp v106, v108, v148 row_shl:15 row_mask:0xf bank_mask:0xf bound_ctrl:0
	v_fmac_f32_dpp v106, v108, v144 row_shl:14 row_mask:0xf bank_mask:0xf
	v_fmac_f32_dpp v106, v158, v148 row_shr:1 row_mask:0xf bank_mask:0xf
	v_fmac_f32_dpp v106, v158, v144 row_shr:2 row_mask:0xf bank_mask:0xf
	s_nop 0
	v_add_f32_e32 v164, v164, v106
	v_mul_f32_dpp v106, v109, v149 row_shl:15 row_mask:0xf bank_mask:0xf bound_ctrl:0
	v_fmac_f32_dpp v106, v109, v145 row_shl:14 row_mask:0xf bank_mask:0xf
	v_fmac_f32_dpp v106, v159, v149 row_shr:1 row_mask:0xf bank_mask:0xf
	v_fmac_f32_dpp v106, v159, v145 row_shr:2 row_mask:0xf bank_mask:0xf
	s_nop 0
	v_add_f32_e32 v231, v231, v106
	v_add3_u32 v106, s51, v155, v193
	v_fma_f32 v158, v102, v150, v90
	ds_read_b128 v[106:109], v106
	s_waitcnt lgkmcnt(0)
; #define PG8_LAS __attribute__((address_space(3)))
; #define PG8_LDW(BUF, N_, BJ_) do { const unsigned ch_ = (unsigned)((BJ_) * 2816 + c0 + colw + 4 * (N_)) * 4u; \
;             W[BUF][0] = *(const f32x4*)((const char*)cw + ch_); W[BUF][1] = *(const f32x4*)((const char*)cw + 5632u * 4u + ch_); \
;             W[BUF][2] = *(const f32x4*)((const char*)cw + 2u * 5632u * 4u + ch_); W[BUF][3] = *(const f32x4*)((const char*)cb + ch_); } while (0)
;     __device__ __forceinline__ void operator()(f32x4 (&acc)[2][2][4][2], const Unit& u, int wr, int wc, int fr_, int fq_) const {
;     ...
;                 if (gi == 0) PG8_LDW(1, 0, 1); else if (gi == 1) PG8_LDW(0, 1, 0); else if (gi == 2) PG8_LDW(1, 1, 1);
;                 const f32x4 w0 = W[gi & 1][0], w1 = W[gi & 1][1], w2 = W[gi & 1][2], bb = W[gi & 1][3];
; #pragma unroll
;                 for (int ai = 0; ai < 2; ++ai) {
;                     f32x4 prev;
;                     if (ai == 0 && wr == 0) prev = (f32x4){0.f, 0.f, 0.f, 0.f};
;                     else prev = *(const PG8_LAS f32x4*)(hal + (((ai * 2 + wr - 1) * 2 + hrow) * 256 + bj * 128 + colw + 4 * n));
; #pragma unroll
;                     for (int m = 0; m < 4; ++m) { const f32x4 cur = acc[ai][bj][m][n]; f32x4 o;
; #pragma unroll
;                         for (int i = 0; i < 4; ++i) {
;                             float s1, s2;
;                             asm volatile("s_nop 1\n\tv_mov_b32_dpp %0, %2 row_ror:1 row_mask:0xf bank_mask:0xf\n\tv_mov_b32_dpp %1, %2 row_ror:2 row_mask:0xf bank_mask:0xf\n\t"
;                                          "v_mov_b32_dpp %0, %3 row_shr:1 row_mask:0xf bank_mask:0xf\n\tv_mov_b32_dpp %1, %3 row_shr:2 row_mask:0xf bank_mask:0xf"
;                                          : "=&v"(s1), "=&v"(s2) : "v"(prev[i]), "v"(cur[i]), "v"(w1[i]), "v"(w0[i]));
;                             float t = bb[i] + w2[i] * cur[i] + w1[i] * s1 + w0[i] * s2; asm volatile("" : "+v"(t)); o[i] = t; }
;                         acc[ai][bj][m][n] = o; prev = cur; __builtin_amdgcn_sched_barrier(0); }
	v_mul_f32_dpp v155, v106, v146 row_shl:15 row_mask:0xf bank_mask:0xf bound_ctrl:0
	v_fmac_f32_dpp v155, v106, v142 row_shl:14 row_mask:0xf bank_mask:0xf
	v_fmac_f32_dpp v155, v102, v146 row_shr:1 row_mask:0xf bank_mask:0xf
	v_fmac_f32_dpp v155, v102, v142 row_shr:2 row_mask:0xf bank_mask:0xf
	v_fma_f32 v159, v103, v151, v91
	v_add_f32_e32 v158, v158, v155
	v_mul_f32_dpp v106, v107, v147 row_shl:15 row_mask:0xf bank_mask:0xf bound_ctrl:0
	v_fmac_f32_dpp v106, v107, v143 row_shl:14 row_mask:0xf bank_mask:0xf
	v_fmac_f32_dpp v106, v103, v147 row_shr:1 row_mask:0xf bank_mask:0xf
	v_fmac_f32_dpp v106, v103, v143 row_shr:2 row_mask:0xf bank_mask:0xf
	v_fma_f32 v232, v104, v152, v92
	v_add_f32_e32 v159, v159, v106
	v_mul_f32_dpp v106, v108, v148 row_shl:15 row_mask:0xf bank_mask:0xf bound_ctrl:0
	v_fmac_f32_dpp v106, v108, v144 row_shl:14 row_mask:0xf bank_mask:0xf
	v_fmac_f32_dpp v106, v104, v148 row_shr:1 row_mask:0xf bank_mask:0xf
	v_fmac_f32_dpp v106, v104, v144 row_shr:2 row_mask:0xf bank_mask:0xf
	v_fma_f32 v238, v105, v153, v93
	v_add_f32_e32 v232, v232, v106
	v_mul_f32_dpp v106, v109, v149 row_shl:15 row_mask:0xf bank_mask:0xf bound_ctrl:0
	v_fmac_f32_dpp v106, v109, v145 row_shl:14 row_mask:0xf bank_mask:0xf
	v_fmac_f32_dpp v106, v105, v149 row_shr:1 row_mask:0xf bank_mask:0xf
	v_fmac_f32_dpp v106, v105, v145 row_shr:2 row_mask:0xf bank_mask:0xf
	s_nop 0
	v_add_f32_e32 v238, v238, v106
	v_fma_f32 v229, v94, v150, v90
	v_mul_f32_dpp v106, v102, v146 row_shl:15 row_mask:0xf bank_mask:0xf bound_ctrl:0
	v_fmac_f32_dpp v106, v102, v142 row_shl:14 row_mask:0xf bank_mask:0xf
	v_fmac_f32_dpp v106, v94, v146 row_shr:1 row_mask:0xf bank_mask:0xf
	v_fmac_f32_dpp v106, v94, v142 row_shr:2 row_mask:0xf bank_mask:0xf
	v_fma_f32 v230, v95, v151, v91
	v_add_f32_e32 v229, v229, v106
	v_mul_f32_dpp v102, v103, v147 row_shl:15 row_mask:0xf bank_mask:0xf bound_ctrl:0
	v_fmac_f32_dpp v102, v103, v143 row_shl:14 row_mask:0xf bank_mask:0xf
	v_fmac_f32_dpp v102, v95, v147 row_shr:1 row_mask:0xf bank_mask:0xf
	v_fmac_f32_dpp v102, v95, v143 row_shr:2 row_mask:0xf bank_mask:0xf
	v_fma_f32 v236, v96, v152, v92
	v_add_f32_e32 v230, v230, v102
	v_mul_f32_dpp v102, v104, v148 row_shl:15 row_mask:0xf bank_mask:0xf bound_ctrl:0
	v_fmac_f32_dpp v102, v104, v144 row_shl:14 row_mask:0xf bank_mask:0xf
	v_fmac_f32_dpp v102, v96, v148 row_shr:1 row_mask:0xf bank_mask:0xf
	v_fmac_f32_dpp v102, v96, v144 row_shr:2 row_mask:0xf bank_mask:0xf
	v_fma_f32 v239, v97, v153, v93
	v_add_f32_e32 v236, v236, v102
	v_mul_f32_dpp v102, v105, v149 row_shl:15 row_mask:0xf bank_mask:0xf bound_ctrl:0
	v_fmac_f32_dpp v102, v105, v145 row_shl:14 row_mask:0xf bank_mask:0xf
	v_fmac_f32_dpp v102, v97, v149 row_shr:1 row_mask:0xf bank_mask:0xf
	v_fmac_f32_dpp v102, v97, v145 row_shr:2 row_mask:0xf bank_mask:0xf
	s_nop 0
	v_add_f32_e32 v239, v239, v102
	v_fma_f32 v233, v50, v150, v90
	v_mul_f32_dpp v102, v94, v146 row_shl:15 row_mask:0xf bank_mask:0xf bound_ctrl:0
	v_fmac_f32_dpp v102, v94, v142 row_shl:14 row_mask:0xf bank_mask:0xf
	v_fmac_f32_dpp v102, v50, v146 row_shr:1 row_mask:0xf bank_mask:0xf
	v_fmac_f32_dpp v102, v50, v142 row_shr:2 row_mask:0xf bank_mask:0xf
	v_fma_f32 v234, v51, v151, v91
	v_add_f32_e32 v233, v233, v102
	v_mul_f32_dpp v94, v95, v147 row_shl:15 row_mask:0xf bank_mask:0xf bound_ctrl:0
	v_fmac_f32_dpp v94, v95, v143 row_shl:14 row_mask:0xf bank_mask:0xf
	v_fmac_f32_dpp v94, v51, v147 row_shr:1 row_mask:0xf bank_mask:0xf
	v_fmac_f32_dpp v94, v51, v143 row_shr:2 row_mask:0xf bank_mask:0xf
	v_fma_f32 v237, v52, v152, v92
	v_add_f32_e32 v234, v234, v94
	v_mul_f32_dpp v94, v96, v148 row_shl:15 row_mask:0xf bank_mask:0xf bound_ctrl:0
	v_fmac_f32_dpp v94, v96, v144 row_shl:14 row_mask:0xf bank_mask:0xf
	v_fmac_f32_dpp v94, v52, v148 row_shr:1 row_mask:0xf bank_mask:0xf
	v_fmac_f32_dpp v94, v52, v144 row_shr:2 row_mask:0xf bank_mask:0xf
	v_fma_f32 v240, v53, v153, v93
	v_add_f32_e32 v237, v237, v94
	v_mul_f32_dpp v94, v97, v149 row_shl:15 row_mask:0xf bank_mask:0xf bound_ctrl:0
	v_fmac_f32_dpp v94, v97, v145 row_shl:14 row_mask:0xf bank_mask:0xf
	v_fmac_f32_dpp v94, v53, v149 row_shr:1 row_mask:0xf bank_mask:0xf
	v_fmac_f32_dpp v94, v53, v145 row_shr:2 row_mask:0xf bank_mask:0xf
	s_nop 0
	v_add_f32_e32 v240, v240, v94
	v_fma_f32 v90, v138, v150, v90
	v_mul_f32_dpp v94, v50, v146 row_shl:15 row_mask:0xf bank_mask:0xf bound_ctrl:0
	v_fmac_f32_dpp v94, v50, v142 row_shl:14 row_mask:0xf bank_mask:0xf
	v_fmac_f32_dpp v94, v138, v146 row_shr:1 row_mask:0xf bank_mask:0xf
	v_fmac_f32_dpp v94, v138, v142 row_shr:2 row_mask:0xf bank_mask:0xf
	v_fma_f32 v91, v139, v151, v91
	v_add_f32_e32 v90, v90, v94
	v_mul_f32_dpp v50, v51, v147 row_shl:15 row_mask:0xf bank_mask:0xf bound_ctrl:0
	v_fmac_f32_dpp v50, v51, v143 row_shl:14 row_mask:0xf bank_mask:0xf
	v_fmac_f32_dpp v50, v139, v147 row_shr:1 row_mask:0xf bank_mask:0xf
	v_fmac_f32_dpp v50, v139, v143 row_shr:2 row_mask:0xf bank_mask:0xf
	v_fma_f32 v92, v140, v152, v92
	v_add_f32_e32 v91, v91, v50
	v_mul_f32_dpp v50, v52, v148 row_shl:15 row_mask:0xf bank_mask:0xf bound_ctrl:0
	v_fmac_f32_dpp v50, v52, v144 row_shl:14 row_mask:0xf bank_mask:0xf
	v_fmac_f32_dpp v50, v140, v148 row_shr:1 row_mask:0xf bank_mask:0xf
	v_fmac_f32_dpp v50, v140, v144 row_shr:2 row_mask:0xf bank_mask:0xf
	v_fmac_f32_e32 v93, v141, v153
	v_add_f32_e32 v92, v92, v50
	v_mul_f32_dpp v50, v53, v149 row_shl:15 row_mask:0xf bank_mask:0xf bound_ctrl:0
	v_fmac_f32_dpp v50, v53, v145 row_shl:14 row_mask:0xf bank_mask:0xf
	v_fmac_f32_dpp v50, v141, v149 row_shr:1 row_mask:0xf bank_mask:0xf
	v_fmac_f32_dpp v50, v141, v145 row_shr:2 row_mask:0xf bank_mask:0xf
	s_nop 0
	v_add_f32_e32 v93, v93, v50
	global_load_dwordx4 v[94:97], v[204:205], off offset:16
	global_load_dwordx4 v[102:105], v195, s[22:23]
	global_load_dwordx4 v[106:109], v195, s[24:25]
	global_load_dwordx4 v[50:53], v[202:203], off offset:16
	s_and_b64 vcc, exec, s[8:9]
	v_mov_b32_e32 v155, 0
	v_mov_b32_e32 v156, 0
	v_mov_b32_e32 v157, 0
	s_cbranch_vccnz .LBB0_672
	ds_read_b128 v[154:157], v226 offset:512
; #define PG8_LAS __attribute__((address_space(3)))
;     __device__ __forceinline__ void operator()(f32x4 (&acc)[2][2][4][2], const Unit& u, int wr, int wc, int fr_, int fq_) const {
;     ...
;                 const f32x4 w0 = W[gi & 1][0], w1 = W[gi & 1][1], w2 = W[gi & 1][2], bb = W[gi & 1][3];
; #pragma unroll
;                 for (int ai = 0; ai < 2; ++ai) {
;                     f32x4 prev;
;                     if (ai == 0 && wr == 0) prev = (f32x4){0.f, 0.f, 0.f, 0.f};
;                     else prev = *(const PG8_LAS f32x4*)(hal + (((ai * 2 + wr - 1) * 2 + hrow) * 256 + bj * 128 + colw + 4 * n));
; #pragma unroll
;                     for (int m = 0; m < 4; ++m) { const f32x4 cur = acc[ai][bj][m][n]; f32x4 o;
; #pragma unroll
;                         for (int i = 0; i < 4; ++i) {
;                             float s1, s2;
;                             asm volatile("s_nop 1\n\tv_mov_b32_dpp %0, %2 row_ror:1 row_mask:0xf bank_mask:0xf\n\tv_mov_b32_dpp %1, %2 row_ror:2 row_mask:0xf bank_mask:0xf\n\t"
;                                          "v_mov_b32_dpp %0, %3 row_shr:1 row_mask:0xf bank_mask:0xf\n\tv_mov_b32_dpp %1, %3 row_shr:2 row_mask:0xf bank_mask:0xf"
;                                          : "=&v"(s1), "=&v"(s2) : "v"(prev[i]), "v"(cur[i]), "v"(w1[i]), "v"(w0[i]));
;                             float t = bb[i] + w2[i] * cur[i] + w1[i] * s1 + w0[i] * s2; asm volatile("" : "+v"(t)); o[i] = t; }
;                         acc[ai][bj][m][n] = o; prev = cur; __builtin_amdgcn_sched_barrier(0); }
.LBB0_672:
	v_mov_b32_e32 v193, v192
	v_pk_mul_f32 v[142:143], v[82:83], v[192:193]
	v_mov_b32_e32 v82, v200
	v_mov_b32_e32 v83, v200
	v_pk_mul_f32 v[76:77], v[76:77], v[82:83]
	v_mov_b32_e32 v82, v198
	v_mov_b32_e32 v83, v198
	v_pk_mul_f32 v[72:73], v[72:73], v[82:83]
	v_mov_b32_e32 v82, v196
	v_mov_b32_e32 v83, v196
	s_waitcnt vmcnt(4)
	v_fma_f32 v144, v134, v126, v98
	v_pk_mul_f32 v[68:69], v[68:69], v[82:83]
	s_waitcnt lgkmcnt(0)
	v_mul_f32_dpp v82, v154, v122 row_shl:15 row_mask:0xf bank_mask:0xf bound_ctrl:0
	v_fmac_f32_dpp v82, v154, v118 row_shl:14 row_mask:0xf bank_mask:0xf
	v_fmac_f32_dpp v82, v134, v122 row_shr:1 row_mask:0xf bank_mask:0xf
	v_fmac_f32_dpp v82, v134, v118 row_shr:2 row_mask:0xf bank_mask:0xf
	v_fma_f32 v145, v135, v127, v99
	v_add_f32_e32 v144, v144, v82
	v_mul_f32_dpp v82, v155, v123 row_shl:15 row_mask:0xf bank_mask:0xf bound_ctrl:0
	v_fmac_f32_dpp v82, v155, v119 row_shl:14 row_mask:0xf bank_mask:0xf
	v_fmac_f32_dpp v82, v135, v123 row_shr:1 row_mask:0xf bank_mask:0xf
	v_fmac_f32_dpp v82, v135, v119 row_shr:2 row_mask:0xf bank_mask:0xf
	v_fma_f32 v146, v136, v128, v100
	v_add_f32_e32 v145, v145, v82
	v_mul_f32_dpp v82, v156, v124 row_shl:15 row_mask:0xf bank_mask:0xf bound_ctrl:0
	v_fmac_f32_dpp v82, v156, v120 row_shl:14 row_mask:0xf bank_mask:0xf
	v_fmac_f32_dpp v82, v136, v124 row_shr:1 row_mask:0xf bank_mask:0xf
	v_fmac_f32_dpp v82, v136, v120 row_shr:2 row_mask:0xf bank_mask:0xf
	v_fma_f32 v147, v137, v129, v101
	v_add_f32_e32 v146, v146, v82
	v_mov_b32_e32 v195, v194
	v_mov_b32_e32 v201, v200
	v_mov_b32_e32 v199, v198
	v_mov_b32_e32 v197, v196
	v_mov_b32_e32 v138, v194
	v_mov_b32_e32 v139, v194
	v_mul_f32_dpp v82, v157, v125 row_shl:15 row_mask:0xf bank_mask:0xf bound_ctrl:0
	v_fmac_f32_dpp v82, v157, v121 row_shl:14 row_mask:0xf bank_mask:0xf
	v_fmac_f32_dpp v82, v137, v125 row_shr:1 row_mask:0xf bank_mask:0xf
	v_fmac_f32_dpp v82, v137, v121 row_shr:2 row_mask:0xf bank_mask:0xf
	s_xor_b64 s[36:37], s[36:37], -1
	v_add_f32_e32 v147, v147, v82
	v_pk_mul_f32 v[138:139], v[88:89], v[138:139]
	v_pk_mul_f32 v[86:87], v[86:87], v[194:195]
	v_mov_b32_e32 v88, v192
	v_mov_b32_e32 v89, v192
	v_pk_mul_f32 v[74:75], v[74:75], v[200:201]
	v_pk_mul_f32 v[70:71], v[70:71], v[198:199]
	v_pk_mul_f32 v[66:67], v[66:67], v[196:197]
	v_pk_mul_f32 v[140:141], v[84:85], v[88:89]
	v_fma_f32 v84, v86, v126, v98
	v_mul_f32_dpp v82, v134, v122 row_shl:15 row_mask:0xf bank_mask:0xf bound_ctrl:0
	v_fmac_f32_dpp v82, v134, v118 row_shl:14 row_mask:0xf bank_mask:0xf
	v_fmac_f32_dpp v82, v86, v122 row_shr:1 row_mask:0xf bank_mask:0xf
	v_fmac_f32_dpp v82, v86, v118 row_shr:2 row_mask:0xf bank_mask:0xf
	v_fma_f32 v89, v138, v128, v100
	v_add_f32_e32 v84, v84, v82
	v_fma_f32 v82, v87, v127, v99
	v_mul_f32_dpp v83, v135, v123 row_shl:15 row_mask:0xf bank_mask:0xf bound_ctrl:0
	v_fmac_f32_dpp v83, v135, v119 row_shl:14 row_mask:0xf bank_mask:0xf
	v_fmac_f32_dpp v83, v87, v123 row_shr:1 row_mask:0xf bank_mask:0xf
	v_fmac_f32_dpp v83, v87, v119 row_shr:2 row_mask:0xf bank_mask:0xf
	v_fma_f32 v135, v139, v129, v101
	v_add_f32_e32 v82, v82, v83
	v_mul_f32_dpp v83, v136, v124 row_shl:15 row_mask:0xf bank_mask:0xf bound_ctrl:0
	v_fmac_f32_dpp v83, v136, v120 row_shl:14 row_mask:0xf bank_mask:0xf
	v_fmac_f32_dpp v83, v138, v124 row_shr:1 row_mask:0xf bank_mask:0xf
	v_fmac_f32_dpp v83, v138, v120 row_shr:2 row_mask:0xf bank_mask:0xf
	s_nop 0
	v_add_f32_e32 v89, v89, v83
	v_mul_f32_dpp v83, v137, v125 row_shl:15 row_mask:0xf bank_mask:0xf bound_ctrl:0
	v_fmac_f32_dpp v83, v137, v121 row_shl:14 row_mask:0xf bank_mask:0xf
	v_fmac_f32_dpp v83, v139, v125 row_shr:1 row_mask:0xf bank_mask:0xf
	v_fmac_f32_dpp v83, v139, v121 row_shr:2 row_mask:0xf bank_mask:0xf
	s_nop 0
	v_add_f32_e32 v135, v135, v83
	v_mul_f32_dpp v83, v86, v122 row_shl:15 row_mask:0xf bank_mask:0xf bound_ctrl:0
	v_fmac_f32_dpp v83, v86, v118 row_shl:14 row_mask:0xf bank_mask:0xf
	v_fmac_f32_dpp v83, v142, v122 row_shr:1 row_mask:0xf bank_mask:0xf
	v_fmac_f32_dpp v83, v142, v118 row_shr:2 row_mask:0xf bank_mask:0xf
	v_fma_f32 v86, v142, v126, v98
	v_add_f32_e32 v86, v86, v83
	v_fma_f32 v83, v143, v127, v99
	v_mul_f32_dpp v85, v87, v123 row_shl:15 row_mask:0xf bank_mask:0xf bound_ctrl:0
	v_fmac_f32_dpp v85, v87, v119 row_shl:14 row_mask:0xf bank_mask:0xf
	v_fmac_f32_dpp v85, v143, v123 row_shr:1 row_mask:0xf bank_mask:0xf
	v_fmac_f32_dpp v85, v143, v119 row_shr:2 row_mask:0xf bank_mask:0xf
	v_fma_f32 v134, v140, v128, v100
	v_add_f32_e32 v83, v83, v85
	v_mul_f32_dpp v85, v138, v124 row_shl:15 row_mask:0xf bank_mask:0xf bound_ctrl:0
	v_fmac_f32_dpp v85, v138, v120 row_shl:14 row_mask:0xf bank_mask:0xf
	v_fmac_f32_dpp v85, v140, v124 row_shr:1 row_mask:0xf bank_mask:0xf
	v_fmac_f32_dpp v85, v140, v120 row_shr:2 row_mask:0xf bank_mask:0xf
	v_fma_f32 v136, v141, v129, v101
	v_add_f32_e32 v134, v134, v85
	v_mul_f32_dpp v85, v139, v125 row_shl:15 row_mask:0xf bank_mask:0xf bound_ctrl:0
	v_fmac_f32_dpp v85, v139, v121 row_shl:14 row_mask:0xf bank_mask:0xf
	v_fmac_f32_dpp v85, v141, v125 row_shr:1 row_mask:0xf bank_mask:0xf
	v_fmac_f32_dpp v85, v141, v121 row_shr:2 row_mask:0xf bank_mask:0xf
	s_nop 0
	v_add_f32_e32 v136, v136, v85
	v_fma_f32 v87, v130, v126, v98
	v_mul_f32_dpp v85, v142, v122 row_shl:15 row_mask:0xf bank_mask:0xf bound_ctrl:0
	v_fmac_f32_dpp v85, v142, v118 row_shl:14 row_mask:0xf bank_mask:0xf
	v_fmac_f32_dpp v85, v130, v122 row_shr:1 row_mask:0xf bank_mask:0xf
	v_fmac_f32_dpp v85, v130, v118 row_shr:2 row_mask:0xf bank_mask:0xf
	v_fma_f32 v137, v133, v129, v101
	v_add_f32_e32 v87, v87, v85
	v_fma_f32 v85, v131, v127, v99
	v_mul_f32_dpp v88, v143, v123 row_shl:15 row_mask:0xf bank_mask:0xf bound_ctrl:0
	v_fmac_f32_dpp v88, v143, v119 row_shl:14 row_mask:0xf bank_mask:0xf
	v_fmac_f32_dpp v88, v131, v123 row_shr:1 row_mask:0xf bank_mask:0xf
	v_fmac_f32_dpp v88, v131, v119 row_shr:2 row_mask:0xf bank_mask:0xf
	v_fma_f32 v131, v132, v128, v100
	v_add_f32_e32 v85, v85, v88
	v_mul_f32_dpp v88, v140, v124 row_shl:15 row_mask:0xf bank_mask:0xf bound_ctrl:0
	v_fmac_f32_dpp v88, v140, v120 row_shl:14 row_mask:0xf bank_mask:0xf
	v_fmac_f32_dpp v88, v132, v124 row_shr:1 row_mask:0xf bank_mask:0xf
	v_fmac_f32_dpp v88, v132, v120 row_shr:2 row_mask:0xf bank_mask:0xf
	s_nop 0
	v_add_f32_e32 v131, v131, v88
	v_mul_f32_dpp v88, v141, v125 row_shl:15 row_mask:0xf bank_mask:0xf bound_ctrl:0
	v_fmac_f32_dpp v88, v141, v121 row_shl:14 row_mask:0xf bank_mask:0xf
	v_fmac_f32_dpp v88, v133, v125 row_shr:1 row_mask:0xf bank_mask:0xf
	v_fmac_f32_dpp v88, v133, v121 row_shr:2 row_mask:0xf bank_mask:0xf
	s_nop 0
	v_add_f32_e32 v137, v137, v88
	v_fma_f32 v130, v74, v126, v98
	ds_read_b128 v[138:141], v226 offset:4608
	s_waitcnt lgkmcnt(0)
; #define PG8_LAS __attribute__((address_space(3)))
; __device__ __forceinline__ unsigned cvt_pk_bf16(float lo, float hi) { unsigned r; asm volatile("v_cvt_pk_bf16_f32 %0, %1, %2" : "=v"(r) : "v"(lo), "v"(hi)); return r; }
;     __device__ __forceinline__ void operator()(f32x4 (&acc)[2][2][4][2], const Unit& u, int wr, int wc, int fr_, int fq_) const {
;     ...
;                     else prev = *(const PG8_LAS f32x4*)(hal + (((ai * 2 + wr - 1) * 2 + hrow) * 256 + bj * 128 + colw + 4 * n));
; #pragma unroll
;                     for (int m = 0; m < 4; ++m) { const f32x4 cur = acc[ai][bj][m][n]; f32x4 o;
; #pragma unroll
;                         for (int i = 0; i < 4; ++i) {
;                             float s1, s2;
;                             asm volatile("s_nop 1\n\tv_mov_b32_dpp %0, %2 row_ror:1 row_mask:0xf bank_mask:0xf\n\tv_mov_b32_dpp %1, %2 row_ror:2 row_mask:0xf bank_mask:0xf\n\t"
;                                          "v_mov_b32_dpp %0, %3 row_shr:1 row_mask:0xf bank_mask:0xf\n\tv_mov_b32_dpp %1, %3 row_shr:2 row_mask:0xf bank_mask:0xf"
;                                          : "=&v"(s1), "=&v"(s2) : "v"(prev[i]), "v"(cur[i]), "v"(w1[i]), "v"(w0[i]));
;                             float t = bb[i] + w2[i] * cur[i] + w1[i] * s1 + w0[i] * s2; asm volatile("" : "+v"(t)); o[i] = t; }
;                         acc[ai][bj][m][n] = o; prev = cur; __builtin_amdgcn_sched_barrier(0); }
;                 }
;                 asm volatile("" ::: "memory"); __builtin_amdgcn_sched_barrier(0);
;             }
; #pragma unroll
;             for (int ai = 0; ai < 2; ++ai)
; #pragma unroll
;                 for (int m = 0; m < 4; ++m) { int rowb = row0; asm volatile("" : "+v"(rowb)); const f32x4 cg = acc[ai][0][m][n], cv = acc[ai][1][m][n]; float res[4];
; #pragma unroll
;                     for (int i = 0; i < 4; ++i) { const float g = cg[i]; res[i] = g * __builtin_amdgcn_rcpf(1.0f + __builtin_amdgcn_exp2f(-1.4426950408889634f * g)) * cv[i]; }
;                     u32x2 w; w.x = cvt_pk_bf16(res[0], res[1]); w.y = cvt_pk_bf16(res[2], res[3]);
;                     const bool skip = (ai == 0) && (m == 0) && (wr == 0) && (fr < 2);
;                     if (!skip) *(u32x2*)((char*)G + ((unsigned)(rowb + ai * HALF + m * 16) * 2816u + (unsigned)(c0 + colw + 4 * n)) * 2u) = w; __builtin_amdgcn_sched_barrier(0); }
	v_mul_f32_dpp v132, v138, v122 row_shl:15 row_mask:0xf bank_mask:0xf bound_ctrl:0
	v_fmac_f32_dpp v132, v138, v118 row_shl:14 row_mask:0xf bank_mask:0xf
	v_fmac_f32_dpp v132, v74, v122 row_shr:1 row_mask:0xf bank_mask:0xf
	v_fmac_f32_dpp v132, v74, v118 row_shr:2 row_mask:0xf bank_mask:0xf
	v_fma_f32 v88, v75, v127, v99
	v_add_f32_e32 v130, v130, v132
	v_mul_f32_dpp v132, v139, v123 row_shl:15 row_mask:0xf bank_mask:0xf bound_ctrl:0
	v_fmac_f32_dpp v132, v139, v119 row_shl:14 row_mask:0xf bank_mask:0xf
	v_fmac_f32_dpp v132, v75, v123 row_shr:1 row_mask:0xf bank_mask:0xf
	v_fmac_f32_dpp v132, v75, v119 row_shr:2 row_mask:0xf bank_mask:0xf
	s_nop 0
	v_add_f32_e32 v88, v88, v132
	v_fma_f32 v133, v76, v128, v100
	v_mul_f32_dpp v132, v140, v124 row_shl:15 row_mask:0xf bank_mask:0xf bound_ctrl:0
	v_fmac_f32_dpp v132, v140, v120 row_shl:14 row_mask:0xf bank_mask:0xf
	v_fmac_f32_dpp v132, v76, v124 row_shr:1 row_mask:0xf bank_mask:0xf
	v_fmac_f32_dpp v132, v76, v120 row_shr:2 row_mask:0xf bank_mask:0xf
	s_nop 0
	v_add_f32_e32 v133, v133, v132
	v_fma_f32 v138, v77, v129, v101
	v_mul_f32_dpp v132, v141, v125 row_shl:15 row_mask:0xf bank_mask:0xf bound_ctrl:0
	v_fmac_f32_dpp v132, v141, v121 row_shl:14 row_mask:0xf bank_mask:0xf
	v_fmac_f32_dpp v132, v77, v125 row_shr:1 row_mask:0xf bank_mask:0xf
	v_fmac_f32_dpp v132, v77, v121 row_shr:2 row_mask:0xf bank_mask:0xf
	s_nop 0
	v_add_f32_e32 v138, v138, v132
	v_fma_f32 v132, v70, v126, v98
	v_mul_f32_dpp v139, v74, v122 row_shl:15 row_mask:0xf bank_mask:0xf bound_ctrl:0
	v_fmac_f32_dpp v139, v74, v118 row_shl:14 row_mask:0xf bank_mask:0xf
	v_fmac_f32_dpp v139, v70, v122 row_shr:1 row_mask:0xf bank_mask:0xf
	v_fmac_f32_dpp v139, v70, v118 row_shr:2 row_mask:0xf bank_mask:0xf
	v_fma_f32 v74, v71, v127, v99
	v_add_f32_e32 v132, v132, v139
	v_mul_f32_dpp v139, v75, v123 row_shl:15 row_mask:0xf bank_mask:0xf bound_ctrl:0
	v_fmac_f32_dpp v139, v75, v119 row_shl:14 row_mask:0xf bank_mask:0xf
	v_fmac_f32_dpp v139, v71, v123 row_shr:1 row_mask:0xf bank_mask:0xf
	v_fmac_f32_dpp v139, v71, v119 row_shr:2 row_mask:0xf bank_mask:0xf
	s_nop 0
	v_add_f32_e32 v74, v74, v139
	v_mul_f32_dpp v75, v76, v124 row_shl:15 row_mask:0xf bank_mask:0xf bound_ctrl:0
	v_fmac_f32_dpp v75, v76, v120 row_shl:14 row_mask:0xf bank_mask:0xf
	v_fmac_f32_dpp v75, v72, v124 row_shr:1 row_mask:0xf bank_mask:0xf
	v_fmac_f32_dpp v75, v72, v120 row_shr:2 row_mask:0xf bank_mask:0xf
	v_fma_f32 v76, v72, v128, v100
	v_add_f32_e32 v76, v76, v75
	v_fma_f32 v139, v73, v129, v101
	v_mul_f32_dpp v75, v77, v125 row_shl:15 row_mask:0xf bank_mask:0xf bound_ctrl:0
	v_fmac_f32_dpp v75, v77, v121 row_shl:14 row_mask:0xf bank_mask:0xf
	v_fmac_f32_dpp v75, v73, v125 row_shr:1 row_mask:0xf bank_mask:0xf
	v_fmac_f32_dpp v75, v73, v121 row_shr:2 row_mask:0xf bank_mask:0xf
	s_nop 0
	v_add_f32_e32 v139, v139, v75
	v_fma_f32 v75, v66, v126, v98
	v_mul_f32_dpp v77, v70, v122 row_shl:15 row_mask:0xf bank_mask:0xf bound_ctrl:0
	v_fmac_f32_dpp v77, v70, v118 row_shl:14 row_mask:0xf bank_mask:0xf
	v_fmac_f32_dpp v77, v66, v122 row_shr:1 row_mask:0xf bank_mask:0xf
	v_fmac_f32_dpp v77, v66, v118 row_shr:2 row_mask:0xf bank_mask:0xf
	v_fma_f32 v70, v67, v127, v99
	v_add_f32_e32 v75, v75, v77
	v_mul_f32_dpp v77, v71, v123 row_shl:15 row_mask:0xf bank_mask:0xf bound_ctrl:0
	v_fmac_f32_dpp v77, v71, v119 row_shl:14 row_mask:0xf bank_mask:0xf
	v_fmac_f32_dpp v77, v67, v123 row_shr:1 row_mask:0xf bank_mask:0xf
	v_fmac_f32_dpp v77, v67, v119 row_shr:2 row_mask:0xf bank_mask:0xf
	s_nop 0
	v_add_f32_e32 v70, v70, v77
	v_fma_f32 v77, v68, v128, v100
	v_mul_f32_dpp v71, v72, v124 row_shl:15 row_mask:0xf bank_mask:0xf bound_ctrl:0
	v_fmac_f32_dpp v71, v72, v120 row_shl:14 row_mask:0xf bank_mask:0xf
	v_fmac_f32_dpp v71, v68, v124 row_shr:1 row_mask:0xf bank_mask:0xf
	v_fmac_f32_dpp v71, v68, v120 row_shr:2 row_mask:0xf bank_mask:0xf
	s_nop 0
	v_add_f32_e32 v77, v77, v71
	v_mul_f32_dpp v71, v73, v125 row_shl:15 row_mask:0xf bank_mask:0xf bound_ctrl:0
	v_fmac_f32_dpp v71, v73, v121 row_shl:14 row_mask:0xf bank_mask:0xf
	v_fmac_f32_dpp v71, v69, v125 row_shr:1 row_mask:0xf bank_mask:0xf
	v_fmac_f32_dpp v71, v69, v121 row_shr:2 row_mask:0xf bank_mask:0xf
	v_fma_f32 v73, v69, v129, v101
	v_add_f32_e32 v73, v73, v71
	v_fma_f32 v72, v110, v126, v98
	v_mul_f32_dpp v71, v66, v122 row_shl:15 row_mask:0xf bank_mask:0xf bound_ctrl:0
	v_fmac_f32_dpp v71, v66, v118 row_shl:14 row_mask:0xf bank_mask:0xf
	v_fmac_f32_dpp v71, v110, v122 row_shr:1 row_mask:0xf bank_mask:0xf
	v_fmac_f32_dpp v71, v110, v118 row_shr:2 row_mask:0xf bank_mask:0xf
	v_fmac_f32_e32 v101, v113, v129
	v_add_f32_e32 v72, v72, v71
	v_fma_f32 v71, v111, v127, v99
	v_mul_f32_dpp v66, v67, v123 row_shl:15 row_mask:0xf bank_mask:0xf bound_ctrl:0
	v_fmac_f32_dpp v66, v67, v119 row_shl:14 row_mask:0xf bank_mask:0xf
	v_fmac_f32_dpp v66, v111, v123 row_shr:1 row_mask:0xf bank_mask:0xf
	v_fmac_f32_dpp v66, v111, v119 row_shr:2 row_mask:0xf bank_mask:0xf
	s_nop 0
	v_add_f32_e32 v71, v71, v66
	v_mul_f32_dpp v66, v68, v124 row_shl:15 row_mask:0xf bank_mask:0xf bound_ctrl:0
	v_fmac_f32_dpp v66, v68, v120 row_shl:14 row_mask:0xf bank_mask:0xf
	v_fmac_f32_dpp v66, v112, v124 row_shr:1 row_mask:0xf bank_mask:0xf
	v_fmac_f32_dpp v66, v112, v120 row_shr:2 row_mask:0xf bank_mask:0xf
	v_fma_f32 v68, v112, v128, v100
	v_add_f32_e32 v68, v68, v66
	v_mul_f32_dpp v66, v69, v125 row_shl:15 row_mask:0xf bank_mask:0xf bound_ctrl:0
	v_fmac_f32_dpp v66, v69, v121 row_shl:14 row_mask:0xf bank_mask:0xf
	v_fmac_f32_dpp v66, v113, v125 row_shr:1 row_mask:0xf bank_mask:0xf
	v_fmac_f32_dpp v66, v113, v121 row_shr:2 row_mask:0xf bank_mask:0xf
	s_nop 0
	v_add_f32_e32 v101, v101, v66
	v_mul_f32_e32 v66, 0xbfb8aa3b, v227
	v_mul_f32_e32 v67, 0xbfb8aa3b, v165
	v_exp_f32_e32 v66, v66
	v_exp_f32_e32 v67, v67
	v_mul_f32_e32 v98, 0xbfb8aa3b, v166
	v_mul_f32_e32 v99, 0xbfb8aa3b, v235
	v_exp_f32_e32 v98, v98
	v_exp_f32_e32 v99, v99
	v_add_f32_e32 v66, 1.0, v66
	v_add_f32_e32 v67, 1.0, v67
	v_rcp_f32_e32 v66, v66
	v_rcp_f32_e32 v67, v67
	v_add_f32_e32 v98, 1.0, v98
	v_add_f32_e32 v99, 1.0, v99
	v_rcp_f32_e32 v98, v98
	v_rcp_f32_e32 v99, v99
	v_mul_f32_e32 v66, v227, v66
	v_mul_f32_e32 v67, v165, v67
	v_mov_b32_e32 v69, v225
	v_mul_f32_e32 v66, v66, v144
	v_mul_f32_e32 v67, v67, v145
	v_mul_f32_e32 v98, v166, v98
	v_mul_f32_e32 v99, v235, v99
	v_mul_f32_e32 v98, v98, v146
	v_mul_f32_e32 v99, v99, v147
	v_cvt_pk_bf16_f32 v66, v66, v67
	v_cvt_pk_bf16_f32 v67, v98, v99
	s_and_saveexec_b64 s[38:39], s[36:37]
	s_cbranch_execz .LBB0_674
	v_mul_lo_u32 v69, v69, s56
	v_add_lshl_u32 v69, v69, v190, 1
	global_store_dwordx2 v69, v[66:67], s[90:91]

; #define PG8_LAS __attribute__((address_space(3)))
; #define PG8_LDW(BUF, N_, BJ_) do { const unsigned ch_ = (unsigned)((BJ_) * 2816 + c0 + colw + 4 * (N_)) * 4u; \
;             W[BUF][0] = *(const f32x4*)((const char*)cw + ch_); W[BUF][1] = *(const f32x4*)((const char*)cw + 5632u * 4u + ch_); \
;             W[BUF][2] = *(const f32x4*)((const char*)cw + 2u * 5632u * 4u + ch_); W[BUF][3] = *(const f32x4*)((const char*)cb + ch_); } while (0)
;     __device__ __forceinline__ void operator()(f32x4 (&acc)[2][2][4][2], const Unit& u, int wr, int wc, int fr_, int fq_) const {
;     ...
;                 if (gi == 0) PG8_LDW(1, 0, 1); else if (gi == 1) PG8_LDW(0, 1, 0); else if (gi == 2) PG8_LDW(1, 1, 1);
;                 const f32x4 w0 = W[gi & 1][0], w1 = W[gi & 1][1], w2 = W[gi & 1][2], bb = W[gi & 1][3];
; #pragma unroll
;                 for (int ai = 0; ai < 2; ++ai) {
;                     f32x4 prev;
;                     if (ai == 0 && wr == 0) prev = (f32x4){0.f, 0.f, 0.f, 0.f};
;                     else prev = *(const PG8_LAS f32x4*)(hal + (((ai * 2 + wr - 1) * 2 + hrow) * 256 + bj * 128 + colw + 4 * n));
; #pragma unroll
;                     for (int m = 0; m < 4; ++m) { const f32x4 cur = acc[ai][bj][m][n]; f32x4 o;
; #pragma unroll
;                         for (int i = 0; i < 4; ++i) {
;                             float s1, s2;
;                             asm volatile("s_nop 1\n\tv_mov_b32_dpp %0, %2 row_ror:1 row_mask:0xf bank_mask:0xf\n\tv_mov_b32_dpp %1, %2 row_ror:2 row_mask:0xf bank_mask:0xf\n\t"
;                                          "v_mov_b32_dpp %0, %3 row_shr:1 row_mask:0xf bank_mask:0xf\n\tv_mov_b32_dpp %1, %3 row_shr:2 row_mask:0xf bank_mask:0xf"
;                                          : "=&v"(s1), "=&v"(s2) : "v"(prev[i]), "v"(cur[i]), "v"(w1[i]), "v"(w0[i]));
;                             float t = bb[i] + w2[i] * cur[i] + w1[i] * s1 + w0[i] * s2; asm volatile("" : "+v"(t)); o[i] = t; }
;                         acc[ai][bj][m][n] = o; prev = cur; __builtin_amdgcn_sched_barrier(0); }
.LBB0_676:
	s_waitcnt vmcnt(11)
	v_fma_f32 v100, v78, v106, v50
	s_waitcnt lgkmcnt(0)
	v_mul_f32_dpp v87, v88, v102 row_shl:15 row_mask:0xf bank_mask:0xf bound_ctrl:0
	v_fmac_f32_dpp v87, v88, v94 row_shl:14 row_mask:0xf bank_mask:0xf
	v_fmac_f32_dpp v87, v78, v102 row_shr:1 row_mask:0xf bank_mask:0xf
	v_fmac_f32_dpp v87, v78, v94 row_shr:2 row_mask:0xf bank_mask:0xf
	v_fma_f32 v99, v79, v107, v51
	v_add_f32_e32 v100, v100, v87
	v_mul_f32_dpp v87, v89, v103 row_shl:15 row_mask:0xf bank_mask:0xf bound_ctrl:0
	v_fmac_f32_dpp v87, v89, v95 row_shl:14 row_mask:0xf bank_mask:0xf
	v_fmac_f32_dpp v87, v79, v103 row_shr:1 row_mask:0xf bank_mask:0xf
	v_fmac_f32_dpp v87, v79, v95 row_shr:2 row_mask:0xf bank_mask:0xf
	v_fma_f32 v101, v80, v108, v52
	v_add_f32_e32 v99, v99, v87
	v_mul_f32_dpp v87, v90, v104 row_shl:15 row_mask:0xf bank_mask:0xf bound_ctrl:0
	v_fmac_f32_dpp v87, v90, v96 row_shl:14 row_mask:0xf bank_mask:0xf
	v_fmac_f32_dpp v87, v80, v104 row_shr:1 row_mask:0xf bank_mask:0xf
	v_fmac_f32_dpp v87, v80, v96 row_shr:2 row_mask:0xf bank_mask:0xf
	v_mov_b32_e32 v92, v194
	v_add_f32_e32 v101, v101, v87
	v_mov_b32_e32 v93, v194
	v_pk_mul_f32 v[116:117], v[42:43], v[194:195]
	v_mov_b32_e32 v42, v192
	v_mov_b32_e32 v43, v192
	v_pk_mul_f32 v[120:121], v[38:39], v[192:193]
	v_mov_b32_e32 v38, v200
	v_mov_b32_e32 v39, v200
	v_fma_f32 v114, v81, v109, v53
	v_pk_mul_f32 v[112:113], v[44:45], v[92:93]
	v_pk_mul_f32 v[118:119], v[40:41], v[42:43]
	v_pk_mul_f32 v[40:41], v[32:33], v[38:39]
	v_pk_mul_f32 v[44:45], v[30:31], v[200:201]
	v_mov_b32_e32 v30, v198
	v_mov_b32_e32 v31, v198
	v_pk_mul_f32 v[32:33], v[26:27], v[198:199]
	v_mov_b32_e32 v26, v196
	v_mov_b32_e32 v27, v196
	v_mul_f32_dpp v87, v91, v105 row_shl:15 row_mask:0xf bank_mask:0xf bound_ctrl:0
	v_fmac_f32_dpp v87, v91, v97 row_shl:14 row_mask:0xf bank_mask:0xf
	v_fmac_f32_dpp v87, v81, v105 row_shr:1 row_mask:0xf bank_mask:0xf
	v_fmac_f32_dpp v87, v81, v97 row_shr:2 row_mask:0xf bank_mask:0xf
	v_pk_mul_f32 v[28:29], v[28:29], v[30:31]
	v_add_f32_e32 v114, v114, v87
	v_pk_mul_f32 v[24:25], v[24:25], v[26:27]
	v_pk_mul_f32 v[22:23], v[22:23], v[196:197]
	v_mul_f32_dpp v87, v78, v102 row_shl:15 row_mask:0xf bank_mask:0xf bound_ctrl:0
	v_fmac_f32_dpp v87, v78, v94 row_shl:14 row_mask:0xf bank_mask:0xf
	v_fmac_f32_dpp v87, v116, v102 row_shr:1 row_mask:0xf bank_mask:0xf
	v_fmac_f32_dpp v87, v116, v94 row_shr:2 row_mask:0xf bank_mask:0xf
	v_fma_f32 v78, v116, v106, v50
	v_add_f32_e32 v78, v78, v87
	v_mul_f32_dpp v87, v79, v103 row_shl:15 row_mask:0xf bank_mask:0xf bound_ctrl:0
	v_fmac_f32_dpp v87, v79, v95 row_shl:14 row_mask:0xf bank_mask:0xf
	v_fmac_f32_dpp v87, v117, v103 row_shr:1 row_mask:0xf bank_mask:0xf
	v_fmac_f32_dpp v87, v117, v95 row_shr:2 row_mask:0xf bank_mask:0xf
	v_fma_f32 v79, v117, v107, v51
	v_add_f32_e32 v79, v79, v87
	v_fma_f32 v90, v112, v108, v52
	v_mul_f32_dpp v87, v80, v104 row_shl:15 row_mask:0xf bank_mask:0xf bound_ctrl:0
	v_fmac_f32_dpp v87, v80, v96 row_shl:14 row_mask:0xf bank_mask:0xf
	v_fmac_f32_dpp v87, v112, v104 row_shr:1 row_mask:0xf bank_mask:0xf
	v_fmac_f32_dpp v87, v112, v96 row_shr:2 row_mask:0xf bank_mask:0xf
	v_fma_f32 v110, v113, v109, v53
	v_add_f32_e32 v90, v90, v87
	v_mul_f32_dpp v80, v81, v105 row_shl:15 row_mask:0xf bank_mask:0xf bound_ctrl:0
	v_fmac_f32_dpp v80, v81, v97 row_shl:14 row_mask:0xf bank_mask:0xf
	v_fmac_f32_dpp v80, v113, v105 row_shr:1 row_mask:0xf bank_mask:0xf
	v_fmac_f32_dpp v80, v113, v97 row_shr:2 row_mask:0xf bank_mask:0xf
	s_nop 0
	v_add_f32_e32 v110, v110, v80
	v_fma_f32 v80, v120, v106, v50
	v_mul_f32_dpp v81, v116, v102 row_shl:15 row_mask:0xf bank_mask:0xf bound_ctrl:0
	v_fmac_f32_dpp v81, v116, v94 row_shl:14 row_mask:0xf bank_mask:0xf
	v_fmac_f32_dpp v81, v120, v102 row_shr:1 row_mask:0xf bank_mask:0xf
	v_fmac_f32_dpp v81, v120, v94 row_shr:2 row_mask:0xf bank_mask:0xf
	v_fma_f32 v91, v118, v108, v52
	v_add_f32_e32 v80, v80, v81
	v_fma_f32 v81, v121, v107, v51
	v_mul_f32_dpp v87, v117, v103 row_shl:15 row_mask:0xf bank_mask:0xf bound_ctrl:0
	v_fmac_f32_dpp v87, v117, v95 row_shl:14 row_mask:0xf bank_mask:0xf
	v_fmac_f32_dpp v87, v121, v103 row_shr:1 row_mask:0xf bank_mask:0xf
	v_fmac_f32_dpp v87, v121, v95 row_shr:2 row_mask:0xf bank_mask:0xf
	v_fma_f32 v111, v119, v109, v53
	v_add_f32_e32 v81, v81, v87
	v_mul_f32_dpp v87, v112, v104 row_shl:15 row_mask:0xf bank_mask:0xf bound_ctrl:0
	v_fmac_f32_dpp v87, v112, v96 row_shl:14 row_mask:0xf bank_mask:0xf
	v_fmac_f32_dpp v87, v118, v104 row_shr:1 row_mask:0xf bank_mask:0xf
	v_fmac_f32_dpp v87, v118, v96 row_shr:2 row_mask:0xf bank_mask:0xf
	s_nop 0
	v_add_f32_e32 v91, v91, v87
	v_mul_f32_dpp v87, v113, v105 row_shl:15 row_mask:0xf bank_mask:0xf bound_ctrl:0
	v_fmac_f32_dpp v87, v113, v97 row_shl:14 row_mask:0xf bank_mask:0xf
	v_fmac_f32_dpp v87, v119, v105 row_shr:1 row_mask:0xf bank_mask:0xf
	v_fmac_f32_dpp v87, v119, v97 row_shr:2 row_mask:0xf bank_mask:0xf
	s_nop 0
	v_add_f32_e32 v111, v111, v87
	v_mul_f32_dpp v87, v120, v102 row_shl:15 row_mask:0xf bank_mask:0xf bound_ctrl:0
	v_fmac_f32_dpp v87, v120, v94 row_shl:14 row_mask:0xf bank_mask:0xf
	v_fmac_f32_dpp v87, v62, v102 row_shr:1 row_mask:0xf bank_mask:0xf
	v_fmac_f32_dpp v87, v62, v94 row_shr:2 row_mask:0xf bank_mask:0xf
	v_fma_f32 v62, v62, v106, v50
	v_add_f32_e32 v62, v62, v87
	v_mul_f32_dpp v87, v121, v103 row_shl:15 row_mask:0xf bank_mask:0xf bound_ctrl:0
	v_fmac_f32_dpp v87, v121, v95 row_shl:14 row_mask:0xf bank_mask:0xf
	v_fmac_f32_dpp v87, v63, v103 row_shr:1 row_mask:0xf bank_mask:0xf
	v_fmac_f32_dpp v87, v63, v95 row_shr:2 row_mask:0xf bank_mask:0xf
	v_fma_f32 v63, v63, v107, v51
	v_add_f32_e32 v63, v63, v87
	v_fma_f32 v98, v64, v108, v52
	v_mul_f32_dpp v87, v118, v104 row_shl:15 row_mask:0xf bank_mask:0xf bound_ctrl:0
	v_fmac_f32_dpp v87, v118, v96 row_shl:14 row_mask:0xf bank_mask:0xf
	v_fmac_f32_dpp v87, v64, v104 row_shr:1 row_mask:0xf bank_mask:0xf
	v_fmac_f32_dpp v87, v64, v96 row_shr:2 row_mask:0xf bank_mask:0xf
	v_fma_f32 v113, v65, v109, v53
	v_add_f32_e32 v98, v98, v87
	v_mul_f32_dpp v64, v119, v105 row_shl:15 row_mask:0xf bank_mask:0xf bound_ctrl:0
	v_fmac_f32_dpp v64, v119, v97 row_shl:14 row_mask:0xf bank_mask:0xf
	v_fmac_f32_dpp v64, v65, v105 row_shr:1 row_mask:0xf bank_mask:0xf
	v_fmac_f32_dpp v64, v65, v97 row_shr:2 row_mask:0xf bank_mask:0xf
	s_nop 0
	v_add_f32_e32 v113, v113, v64
	v_fma_f32 v64, v44, v106, v50
	ds_read_b128 v[116:119], v226 offset:4112
	s_waitcnt lgkmcnt(0)
; #define PG8_LAS __attribute__((address_space(3)))
;     __device__ __forceinline__ void operator()(f32x4 (&acc)[2][2][4][2], const Unit& u, int wr, int wc, int fr_, int fq_) const {
;     ...
;                     f32x4 prev;
;                     if (ai == 0 && wr == 0) prev = (f32x4){0.f, 0.f, 0.f, 0.f};
;                     else prev = *(const PG8_LAS f32x4*)(hal + (((ai * 2 + wr - 1) * 2 + hrow) * 256 + bj * 128 + colw + 4 * n));
; #pragma unroll
;                     for (int m = 0; m < 4; ++m) { const f32x4 cur = acc[ai][bj][m][n]; f32x4 o;
; #pragma unroll
;                         for (int i = 0; i < 4; ++i) {
;                             float s1, s2;
;                             asm volatile("s_nop 1\n\tv_mov_b32_dpp %0, %2 row_ror:1 row_mask:0xf bank_mask:0xf\n\tv_mov_b32_dpp %1, %2 row_ror:2 row_mask:0xf bank_mask:0xf\n\t"
;                                          "v_mov_b32_dpp %0, %3 row_shr:1 row_mask:0xf bank_mask:0xf\n\tv_mov_b32_dpp %1, %3 row_shr:2 row_mask:0xf bank_mask:0xf"
;                                          : "=&v"(s1), "=&v"(s2) : "v"(prev[i]), "v"(cur[i]), "v"(w1[i]), "v"(w0[i]));
;                             float t = bb[i] + w2[i] * cur[i] + w1[i] * s1 + w0[i] * s2; asm volatile("" : "+v"(t)); o[i] = t; }
;                         acc[ai][bj][m][n] = o; prev = cur; __builtin_amdgcn_sched_barrier(0); }
	v_mul_f32_dpp v87, v116, v102 row_shl:15 row_mask:0xf bank_mask:0xf bound_ctrl:0
	v_fmac_f32_dpp v87, v116, v94 row_shl:14 row_mask:0xf bank_mask:0xf
	v_fmac_f32_dpp v87, v44, v102 row_shr:1 row_mask:0xf bank_mask:0xf
	v_fmac_f32_dpp v87, v44, v94 row_shr:2 row_mask:0xf bank_mask:0xf
	v_fma_f32 v65, v45, v107, v51
	v_add_f32_e32 v64, v64, v87
	v_mul_f32_dpp v87, v117, v103 row_shl:15 row_mask:0xf bank_mask:0xf bound_ctrl:0
	v_fmac_f32_dpp v87, v117, v95 row_shl:14 row_mask:0xf bank_mask:0xf
	v_fmac_f32_dpp v87, v45, v103 row_shr:1 row_mask:0xf bank_mask:0xf
	v_fmac_f32_dpp v87, v45, v95 row_shr:2 row_mask:0xf bank_mask:0xf
	v_fma_f32 v112, v40, v108, v52
	v_add_f32_e32 v65, v65, v87
	v_mul_f32_dpp v87, v118, v104 row_shl:15 row_mask:0xf bank_mask:0xf bound_ctrl:0
	v_fmac_f32_dpp v87, v118, v96 row_shl:14 row_mask:0xf bank_mask:0xf
	v_fmac_f32_dpp v87, v40, v104 row_shr:1 row_mask:0xf bank_mask:0xf
	v_fmac_f32_dpp v87, v40, v96 row_shr:2 row_mask:0xf bank_mask:0xf
	v_fma_f32 v115, v41, v109, v53
	v_add_f32_e32 v112, v112, v87
	v_mul_f32_dpp v87, v119, v105 row_shl:15 row_mask:0xf bank_mask:0xf bound_ctrl:0
	v_fmac_f32_dpp v87, v119, v97 row_shl:14 row_mask:0xf bank_mask:0xf
	v_fmac_f32_dpp v87, v41, v105 row_shr:1 row_mask:0xf bank_mask:0xf
	v_fmac_f32_dpp v87, v41, v97 row_shr:2 row_mask:0xf bank_mask:0xf
	s_nop 0
	v_add_f32_e32 v115, v115, v87
	v_mul_f32_dpp v87, v44, v102 row_shl:15 row_mask:0xf bank_mask:0xf bound_ctrl:0
	v_fmac_f32_dpp v87, v44, v94 row_shl:14 row_mask:0xf bank_mask:0xf
	v_fmac_f32_dpp v87, v32, v102 row_shr:1 row_mask:0xf bank_mask:0xf
	v_fmac_f32_dpp v87, v32, v94 row_shr:2 row_mask:0xf bank_mask:0xf
	v_fma_f32 v44, v32, v106, v50
	v_add_f32_e32 v44, v44, v87
	v_mul_f32_dpp v87, v45, v103 row_shl:15 row_mask:0xf bank_mask:0xf bound_ctrl:0
	v_fmac_f32_dpp v87, v45, v95 row_shl:14 row_mask:0xf bank_mask:0xf
	v_fmac_f32_dpp v87, v33, v103 row_shr:1 row_mask:0xf bank_mask:0xf
	v_fmac_f32_dpp v87, v33, v95 row_shr:2 row_mask:0xf bank_mask:0xf
	v_fma_f32 v45, v33, v107, v51
	v_add_f32_e32 v45, v45, v87
	v_mul_f32_dpp v87, v40, v104 row_shl:15 row_mask:0xf bank_mask:0xf bound_ctrl:0
	v_fmac_f32_dpp v87, v40, v96 row_shl:14 row_mask:0xf bank_mask:0xf
	v_fmac_f32_dpp v87, v28, v104 row_shr:1 row_mask:0xf bank_mask:0xf
	v_fmac_f32_dpp v87, v28, v96 row_shr:2 row_mask:0xf bank_mask:0xf
	v_fma_f32 v40, v28, v108, v52
	v_add_f32_e32 v40, v40, v87
	v_mul_f32_dpp v87, v41, v105 row_shl:15 row_mask:0xf bank_mask:0xf bound_ctrl:0
	v_fmac_f32_dpp v87, v41, v97 row_shl:14 row_mask:0xf bank_mask:0xf
	v_fmac_f32_dpp v87, v29, v105 row_shr:1 row_mask:0xf bank_mask:0xf
	v_fmac_f32_dpp v87, v29, v97 row_shr:2 row_mask:0xf bank_mask:0xf
	v_fma_f32 v41, v29, v109, v53
	v_add_f32_e32 v41, v41, v87
	v_mul_f32_dpp v87, v32, v102 row_shl:15 row_mask:0xf bank_mask:0xf bound_ctrl:0
	v_fmac_f32_dpp v87, v32, v94 row_shl:14 row_mask:0xf bank_mask:0xf
	v_fmac_f32_dpp v87, v22, v102 row_shr:1 row_mask:0xf bank_mask:0xf
	v_fmac_f32_dpp v87, v22, v94 row_shr:2 row_mask:0xf bank_mask:0xf
	v_fma_f32 v32, v22, v106, v50
	v_add_f32_e32 v32, v32, v87
	v_mul_f32_dpp v87, v33, v103 row_shl:15 row_mask:0xf bank_mask:0xf bound_ctrl:0
	v_fmac_f32_dpp v87, v33, v95 row_shl:14 row_mask:0xf bank_mask:0xf
	v_fmac_f32_dpp v87, v23, v103 row_shr:1 row_mask:0xf bank_mask:0xf
	v_fmac_f32_dpp v87, v23, v95 row_shr:2 row_mask:0xf bank_mask:0xf
	v_fma_f32 v33, v23, v107, v51
	v_add_f32_e32 v33, v33, v87
	v_mul_f32_dpp v87, v28, v104 row_shl:15 row_mask:0xf bank_mask:0xf bound_ctrl:0
	v_fmac_f32_dpp v87, v28, v96 row_shl:14 row_mask:0xf bank_mask:0xf
	v_fmac_f32_dpp v87, v24, v104 row_shr:1 row_mask:0xf bank_mask:0xf
	v_fmac_f32_dpp v87, v24, v96 row_shr:2 row_mask:0xf bank_mask:0xf
	v_fma_f32 v28, v24, v108, v52
	v_add_f32_e32 v28, v28, v87
	v_mul_f32_dpp v87, v29, v105 row_shl:15 row_mask:0xf bank_mask:0xf bound_ctrl:0
	v_fmac_f32_dpp v87, v29, v97 row_shl:14 row_mask:0xf bank_mask:0xf
	v_fmac_f32_dpp v87, v25, v105 row_shr:1 row_mask:0xf bank_mask:0xf
	v_fmac_f32_dpp v87, v25, v97 row_shr:2 row_mask:0xf bank_mask:0xf
	v_fma_f32 v29, v25, v109, v53
	v_add_f32_e32 v29, v29, v87
	v_mul_f32_dpp v87, v22, v102 row_shl:15 row_mask:0xf bank_mask:0xf bound_ctrl:0
	v_fmac_f32_dpp v87, v22, v94 row_shl:14 row_mask:0xf bank_mask:0xf
	v_fmac_f32_dpp v87, v58, v102 row_shr:1 row_mask:0xf bank_mask:0xf
	v_fmac_f32_dpp v87, v58, v94 row_shr:2 row_mask:0xf bank_mask:0xf
	v_fma_f32 v22, v58, v106, v50
	v_add_f32_e32 v22, v22, v87
	v_mul_f32_dpp v50, v23, v103 row_shl:15 row_mask:0xf bank_mask:0xf bound_ctrl:0
	v_fmac_f32_dpp v50, v23, v95 row_shl:14 row_mask:0xf bank_mask:0xf
	v_fmac_f32_dpp v50, v59, v103 row_shr:1 row_mask:0xf bank_mask:0xf
	v_fmac_f32_dpp v50, v59, v95 row_shr:2 row_mask:0xf bank_mask:0xf
	v_fma_f32 v23, v59, v107, v51
	v_add_f32_e32 v23, v23, v50
	v_mul_f32_dpp v50, v24, v104 row_shl:15 row_mask:0xf bank_mask:0xf bound_ctrl:0
	v_fmac_f32_dpp v50, v24, v96 row_shl:14 row_mask:0xf bank_mask:0xf
	v_fmac_f32_dpp v50, v60, v104 row_shr:1 row_mask:0xf bank_mask:0xf
	v_fmac_f32_dpp v50, v60, v96 row_shr:2 row_mask:0xf bank_mask:0xf
	v_fma_f32 v24, v60, v108, v52
	v_add_f32_e32 v24, v24, v50
	v_fmac_f32_e32 v53, v61, v109
	v_mul_f32_dpp v50, v25, v105 row_shl:15 row_mask:0xf bank_mask:0xf bound_ctrl:0
	v_fmac_f32_dpp v50, v25, v97 row_shl:14 row_mask:0xf bank_mask:0xf
	v_fmac_f32_dpp v50, v61, v105 row_shr:1 row_mask:0xf bank_mask:0xf
	v_fmac_f32_dpp v50, v61, v97 row_shr:2 row_mask:0xf bank_mask:0xf
	s_nop 0
	v_add_f32_e32 v53, v53, v50
	s_and_b64 vcc, exec, s[8:9]
	v_mov_b32_e32 v87, 0
	v_mov_b32_e32 v88, 0
	v_mov_b32_e32 v89, 0
	s_cbranch_vccnz .LBB0_678
	ds_read_b128 v[86:89], v226 offset:528
; #define PG8_LAS __attribute__((address_space(3)))
;     __device__ __forceinline__ void operator()(f32x4 (&acc)[2][2][4][2], const Unit& u, int wr, int wc, int fr_, int fq_) const {
;     ...
;                 const f32x4 w0 = W[gi & 1][0], w1 = W[gi & 1][1], w2 = W[gi & 1][2], bb = W[gi & 1][3];
; #pragma unroll
;                 for (int ai = 0; ai < 2; ++ai) {
;                     f32x4 prev;
;                     if (ai == 0 && wr == 0) prev = (f32x4){0.f, 0.f, 0.f, 0.f};
;                     else prev = *(const PG8_LAS f32x4*)(hal + (((ai * 2 + wr - 1) * 2 + hrow) * 256 + bj * 128 + colw + 4 * n));
; #pragma unroll
;                     for (int m = 0; m < 4; ++m) { const f32x4 cur = acc[ai][bj][m][n]; f32x4 o;
; #pragma unroll
;                         for (int i = 0; i < 4; ++i) {
;                             float s1, s2;
;                             asm volatile("s_nop 1\n\tv_mov_b32_dpp %0, %2 row_ror:1 row_mask:0xf bank_mask:0xf\n\tv_mov_b32_dpp %1, %2 row_ror:2 row_mask:0xf bank_mask:0xf\n\t"
;                                          "v_mov_b32_dpp %0, %3 row_shr:1 row_mask:0xf bank_mask:0xf\n\tv_mov_b32_dpp %1, %3 row_shr:2 row_mask:0xf bank_mask:0xf"
;                                          : "=&v"(s1), "=&v"(s2) : "v"(prev[i]), "v"(cur[i]), "v"(w1[i]), "v"(w0[i]));
;                             float t = bb[i] + w2[i] * cur[i] + w1[i] * s1 + w0[i] * s2; asm volatile("" : "+v"(t)); o[i] = t; }
;                         acc[ai][bj][m][n] = o; prev = cur; __builtin_amdgcn_sched_barrier(0); }
.LBB0_678:
	s_waitcnt vmcnt(0)
	v_fma_f32 v52, v54, v82, v66
	v_pk_mul_f32 v[58:59], v[14:15], v[192:193]
	s_waitcnt lgkmcnt(0)
	v_mul_f32_dpp v14, v86, v74 row_shl:15 row_mask:0xf bank_mask:0xf bound_ctrl:0
	v_fmac_f32_dpp v14, v86, v70 row_shl:14 row_mask:0xf bank_mask:0xf
	v_fmac_f32_dpp v14, v54, v74 row_shr:1 row_mask:0xf bank_mask:0xf
	v_fmac_f32_dpp v14, v54, v70 row_shr:2 row_mask:0xf bank_mask:0xf
	v_fma_f32 v60, v55, v83, v67
	v_add_f32_e32 v52, v52, v14
	v_mul_f32_dpp v14, v87, v75 row_shl:15 row_mask:0xf bank_mask:0xf bound_ctrl:0
	v_fmac_f32_dpp v14, v87, v71 row_shl:14 row_mask:0xf bank_mask:0xf
	v_fmac_f32_dpp v14, v55, v75 row_shr:1 row_mask:0xf bank_mask:0xf
	v_fmac_f32_dpp v14, v55, v71 row_shr:2 row_mask:0xf bank_mask:0xf
	v_fma_f32 v61, v56, v84, v68
	v_add_f32_e32 v60, v60, v14
	v_mul_f32_dpp v14, v88, v76 row_shl:15 row_mask:0xf bank_mask:0xf bound_ctrl:0
	v_fmac_f32_dpp v14, v88, v72 row_shl:14 row_mask:0xf bank_mask:0xf
	v_fmac_f32_dpp v14, v56, v76 row_shr:1 row_mask:0xf bank_mask:0xf
	v_fmac_f32_dpp v14, v56, v72 row_shr:2 row_mask:0xf bank_mask:0xf
	v_fma_f32 v86, v57, v85, v69
	v_add_f32_e32 v61, v61, v14
	v_mul_f32_dpp v14, v89, v77 row_shl:15 row_mask:0xf bank_mask:0xf bound_ctrl:0
	v_fmac_f32_dpp v14, v89, v73 row_shl:14 row_mask:0xf bank_mask:0xf
	v_fmac_f32_dpp v14, v57, v77 row_shr:1 row_mask:0xf bank_mask:0xf
	v_fmac_f32_dpp v14, v57, v73 row_shr:2 row_mask:0xf bank_mask:0xf
	v_pk_mul_f32 v[18:19], v[18:19], v[194:195]
	v_add_f32_e32 v86, v86, v14
	v_pk_mul_f32 v[42:43], v[16:17], v[42:43]
	v_pk_mul_f32 v[12:13], v[12:13], v[38:39]
	v_pk_mul_f32 v[10:11], v[10:11], v[200:201]
	v_pk_mul_f32 v[8:9], v[8:9], v[30:31]
	v_pk_mul_f32 v[6:7], v[6:7], v[198:199]
	v_pk_mul_f32 v[4:5], v[4:5], v[26:27]
	v_pk_mul_f32 v[2:3], v[2:3], v[196:197]
	v_pk_mul_f32 v[50:51], v[20:21], v[92:93]
	v_fma_f32 v16, v18, v82, v66
	v_mul_f32_dpp v14, v54, v74 row_shl:15 row_mask:0xf bank_mask:0xf bound_ctrl:0
	v_fmac_f32_dpp v14, v54, v70 row_shl:14 row_mask:0xf bank_mask:0xf
	v_fmac_f32_dpp v14, v18, v74 row_shr:1 row_mask:0xf bank_mask:0xf
	v_fmac_f32_dpp v14, v18, v70 row_shr:2 row_mask:0xf bank_mask:0xf
	v_fma_f32 v21, v50, v84, v68
	v_add_f32_e32 v16, v16, v14
	v_fma_f32 v14, v19, v83, v67
	v_mul_f32_dpp v15, v55, v75 row_shl:15 row_mask:0xf bank_mask:0xf bound_ctrl:0
	v_fmac_f32_dpp v15, v55, v71 row_shl:14 row_mask:0xf bank_mask:0xf
	v_fmac_f32_dpp v15, v19, v75 row_shr:1 row_mask:0xf bank_mask:0xf
	v_fmac_f32_dpp v15, v19, v71 row_shr:2 row_mask:0xf bank_mask:0xf
	v_fma_f32 v30, v51, v85, v69
	v_add_f32_e32 v14, v14, v15
	v_mul_f32_dpp v15, v56, v76 row_shl:15 row_mask:0xf bank_mask:0xf bound_ctrl:0
	v_fmac_f32_dpp v15, v56, v72 row_shl:14 row_mask:0xf bank_mask:0xf
	v_fmac_f32_dpp v15, v50, v76 row_shr:1 row_mask:0xf bank_mask:0xf
	v_fmac_f32_dpp v15, v50, v72 row_shr:2 row_mask:0xf bank_mask:0xf
	s_nop 0
	v_add_f32_e32 v21, v21, v15
	v_mul_f32_dpp v15, v57, v77 row_shl:15 row_mask:0xf bank_mask:0xf bound_ctrl:0
	v_fmac_f32_dpp v15, v57, v73 row_shl:14 row_mask:0xf bank_mask:0xf
	v_fmac_f32_dpp v15, v51, v77 row_shr:1 row_mask:0xf bank_mask:0xf
	v_fmac_f32_dpp v15, v51, v73 row_shr:2 row_mask:0xf bank_mask:0xf
	s_nop 0
	v_add_f32_e32 v30, v30, v15
	v_mul_f32_dpp v15, v18, v74 row_shl:15 row_mask:0xf bank_mask:0xf bound_ctrl:0
	v_fmac_f32_dpp v15, v18, v70 row_shl:14 row_mask:0xf bank_mask:0xf
	v_fmac_f32_dpp v15, v58, v74 row_shr:1 row_mask:0xf bank_mask:0xf
	v_fmac_f32_dpp v15, v58, v70 row_shr:2 row_mask:0xf bank_mask:0xf
	v_fma_f32 v18, v58, v82, v66
	v_add_f32_e32 v18, v18, v15
	v_fma_f32 v15, v59, v83, v67
	v_mul_f32_dpp v17, v19, v75 row_shl:15 row_mask:0xf bank_mask:0xf bound_ctrl:0
	v_fmac_f32_dpp v17, v19, v71 row_shl:14 row_mask:0xf bank_mask:0xf
	v_fmac_f32_dpp v17, v59, v75 row_shr:1 row_mask:0xf bank_mask:0xf
	v_fmac_f32_dpp v17, v59, v71 row_shr:2 row_mask:0xf bank_mask:0xf
	v_fma_f32 v25, v42, v84, v68
	v_add_f32_e32 v15, v15, v17
	v_mul_f32_dpp v17, v50, v76 row_shl:15 row_mask:0xf bank_mask:0xf bound_ctrl:0
	v_fmac_f32_dpp v17, v50, v72 row_shl:14 row_mask:0xf bank_mask:0xf
	v_fmac_f32_dpp v17, v42, v76 row_shr:1 row_mask:0xf bank_mask:0xf
	v_fmac_f32_dpp v17, v42, v72 row_shr:2 row_mask:0xf bank_mask:0xf
	v_fma_f32 v38, v43, v85, v69
	v_add_f32_e32 v25, v25, v17
	v_mul_f32_dpp v17, v51, v77 row_shl:15 row_mask:0xf bank_mask:0xf bound_ctrl:0
	v_fmac_f32_dpp v17, v51, v73 row_shl:14 row_mask:0xf bank_mask:0xf
	v_fmac_f32_dpp v17, v43, v77 row_shr:1 row_mask:0xf bank_mask:0xf
	v_fmac_f32_dpp v17, v43, v73 row_shr:2 row_mask:0xf bank_mask:0xf
	s_nop 0
	v_add_f32_e32 v38, v38, v17
	v_fma_f32 v19, v46, v82, v66
	v_mul_f32_dpp v17, v58, v74 row_shl:15 row_mask:0xf bank_mask:0xf bound_ctrl:0
	v_fmac_f32_dpp v17, v58, v70 row_shl:14 row_mask:0xf bank_mask:0xf
	v_fmac_f32_dpp v17, v46, v74 row_shr:1 row_mask:0xf bank_mask:0xf
	v_fmac_f32_dpp v17, v46, v70 row_shr:2 row_mask:0xf bank_mask:0xf
	v_fma_f32 v27, v48, v84, v68
	v_add_f32_e32 v19, v19, v17
	v_fma_f32 v17, v47, v83, v67
	v_mul_f32_dpp v20, v59, v75 row_shl:15 row_mask:0xf bank_mask:0xf bound_ctrl:0
	v_fmac_f32_dpp v20, v59, v71 row_shl:14 row_mask:0xf bank_mask:0xf
	v_fmac_f32_dpp v20, v47, v75 row_shr:1 row_mask:0xf bank_mask:0xf
	v_fmac_f32_dpp v20, v47, v71 row_shr:2 row_mask:0xf bank_mask:0xf
	s_nop 0
	v_add_f32_e32 v17, v17, v20
	v_mul_f32_dpp v20, v42, v76 row_shl:15 row_mask:0xf bank_mask:0xf bound_ctrl:0
	v_fmac_f32_dpp v20, v42, v72 row_shl:14 row_mask:0xf bank_mask:0xf
	v_fmac_f32_dpp v20, v48, v76 row_shr:1 row_mask:0xf bank_mask:0xf
	v_fmac_f32_dpp v20, v48, v72 row_shr:2 row_mask:0xf bank_mask:0xf
	v_fma_f32 v42, v49, v85, v69
	v_add_f32_e32 v27, v27, v20
	v_mul_f32_dpp v20, v43, v77 row_shl:15 row_mask:0xf bank_mask:0xf bound_ctrl:0
	v_fmac_f32_dpp v20, v43, v73 row_shl:14 row_mask:0xf bank_mask:0xf
	v_fmac_f32_dpp v20, v49, v77 row_shr:1 row_mask:0xf bank_mask:0xf
	v_fmac_f32_dpp v20, v49, v73 row_shr:2 row_mask:0xf bank_mask:0xf
	s_nop 0
	v_add_f32_e32 v42, v42, v20
	v_fma_f32 v26, v10, v82, v66
	ds_read_b128 v[46:49], v226 offset:4624
	s_waitcnt lgkmcnt(0)
; __device__ __forceinline__ unsigned cvt_pk_bf16(float lo, float hi) { unsigned r; asm volatile("v_cvt_pk_bf16_f32 %0, %1, %2" : "=v"(r) : "v"(lo), "v"(hi)); return r; }
;     __device__ __forceinline__ void operator()(f32x4 (&acc)[2][2][4][2], const Unit& u, int wr, int wc, int fr_, int fq_) const {
;     ...
;                     for (int m = 0; m < 4; ++m) { const f32x4 cur = acc[ai][bj][m][n]; f32x4 o;
; #pragma unroll
;                         for (int i = 0; i < 4; ++i) {
;                             float s1, s2;
;                             asm volatile("s_nop 1\n\tv_mov_b32_dpp %0, %2 row_ror:1 row_mask:0xf bank_mask:0xf\n\tv_mov_b32_dpp %1, %2 row_ror:2 row_mask:0xf bank_mask:0xf\n\t"
;                                          "v_mov_b32_dpp %0, %3 row_shr:1 row_mask:0xf bank_mask:0xf\n\tv_mov_b32_dpp %1, %3 row_shr:2 row_mask:0xf bank_mask:0xf"
;                                          : "=&v"(s1), "=&v"(s2) : "v"(prev[i]), "v"(cur[i]), "v"(w1[i]), "v"(w0[i]));
;                             float t = bb[i] + w2[i] * cur[i] + w1[i] * s1 + w0[i] * s2; asm volatile("" : "+v"(t)); o[i] = t; }
;                         acc[ai][bj][m][n] = o; prev = cur; __builtin_amdgcn_sched_barrier(0); }
;                 }
;                 asm volatile("" ::: "memory"); __builtin_amdgcn_sched_barrier(0);
;             }
; #pragma unroll
;             for (int ai = 0; ai < 2; ++ai)
; #pragma unroll
;                 for (int m = 0; m < 4; ++m) { int rowb = row0; asm volatile("" : "+v"(rowb)); const f32x4 cg = acc[ai][0][m][n], cv = acc[ai][1][m][n]; float res[4];
; #pragma unroll
;                     for (int i = 0; i < 4; ++i) { const float g = cg[i]; res[i] = g * __builtin_amdgcn_rcpf(1.0f + __builtin_amdgcn_exp2f(-1.4426950408889634f * g)) * cv[i]; }
;                     u32x2 w; w.x = cvt_pk_bf16(res[0], res[1]); w.y = cvt_pk_bf16(res[2], res[3]);
;                     const bool skip = (ai == 0) && (m == 0) && (wr == 0) && (fr < 2);
;                     if (!skip) *(u32x2*)((char*)G + ((unsigned)(rowb + ai * HALF + m * 16) * 2816u + (unsigned)(c0 + colw + 4 * n)) * 2u) = w; __builtin_amdgcn_sched_barrier(0); }
	v_mul_f32_dpp v31, v46, v74 row_shl:15 row_mask:0xf bank_mask:0xf bound_ctrl:0
	v_fmac_f32_dpp v31, v46, v70 row_shl:14 row_mask:0xf bank_mask:0xf
	v_fmac_f32_dpp v31, v10, v74 row_shr:1 row_mask:0xf bank_mask:0xf
	v_fmac_f32_dpp v31, v10, v70 row_shr:2 row_mask:0xf bank_mask:0xf
	v_fma_f32 v20, v11, v83, v67
	v_add_f32_e32 v26, v26, v31
	v_mul_f32_dpp v31, v47, v75 row_shl:15 row_mask:0xf bank_mask:0xf bound_ctrl:0
	v_fmac_f32_dpp v31, v47, v71 row_shl:14 row_mask:0xf bank_mask:0xf
	v_fmac_f32_dpp v31, v11, v75 row_shr:1 row_mask:0xf bank_mask:0xf
	v_fmac_f32_dpp v31, v11, v71 row_shr:2 row_mask:0xf bank_mask:0xf
	s_nop 0
	v_add_f32_e32 v20, v20, v31
	v_fma_f32 v39, v12, v84, v68
	v_mul_f32_dpp v31, v48, v76 row_shl:15 row_mask:0xf bank_mask:0xf bound_ctrl:0
	v_fmac_f32_dpp v31, v48, v72 row_shl:14 row_mask:0xf bank_mask:0xf
	v_fmac_f32_dpp v31, v12, v76 row_shr:1 row_mask:0xf bank_mask:0xf
	v_fmac_f32_dpp v31, v12, v72 row_shr:2 row_mask:0xf bank_mask:0xf
	s_nop 0
	v_add_f32_e32 v39, v39, v31
	v_fma_f32 v43, v13, v85, v69
	v_mul_f32_dpp v31, v49, v77 row_shl:15 row_mask:0xf bank_mask:0xf bound_ctrl:0
	v_fmac_f32_dpp v31, v49, v73 row_shl:14 row_mask:0xf bank_mask:0xf
	v_fmac_f32_dpp v31, v13, v77 row_shr:1 row_mask:0xf bank_mask:0xf
	v_fmac_f32_dpp v31, v13, v73 row_shr:2 row_mask:0xf bank_mask:0xf
	s_nop 0
	v_add_f32_e32 v43, v43, v31
	v_fma_f32 v31, v6, v82, v66
	v_mul_f32_dpp v46, v10, v74 row_shl:15 row_mask:0xf bank_mask:0xf bound_ctrl:0
	v_fmac_f32_dpp v46, v10, v70 row_shl:14 row_mask:0xf bank_mask:0xf
	v_fmac_f32_dpp v46, v6, v74 row_shr:1 row_mask:0xf bank_mask:0xf
	v_fmac_f32_dpp v46, v6, v70 row_shr:2 row_mask:0xf bank_mask:0xf
	v_fma_f32 v10, v7, v83, v67
	v_add_f32_e32 v31, v31, v46
	v_mul_f32_dpp v46, v11, v75 row_shl:15 row_mask:0xf bank_mask:0xf bound_ctrl:0
	v_fmac_f32_dpp v46, v11, v71 row_shl:14 row_mask:0xf bank_mask:0xf
	v_fmac_f32_dpp v46, v7, v75 row_shr:1 row_mask:0xf bank_mask:0xf
	v_fmac_f32_dpp v46, v7, v71 row_shr:2 row_mask:0xf bank_mask:0xf
	s_nop 0
	v_add_f32_e32 v10, v10, v46
	v_mul_f32_dpp v11, v12, v76 row_shl:15 row_mask:0xf bank_mask:0xf bound_ctrl:0
	v_fmac_f32_dpp v11, v12, v72 row_shl:14 row_mask:0xf bank_mask:0xf
	v_fmac_f32_dpp v11, v8, v76 row_shr:1 row_mask:0xf bank_mask:0xf
	v_fmac_f32_dpp v11, v8, v72 row_shr:2 row_mask:0xf bank_mask:0xf
	v_fma_f32 v12, v8, v84, v68
	v_add_f32_e32 v12, v12, v11
	v_fma_f32 v46, v9, v85, v69
	v_mul_f32_dpp v11, v13, v77 row_shl:15 row_mask:0xf bank_mask:0xf bound_ctrl:0
	v_fmac_f32_dpp v11, v13, v73 row_shl:14 row_mask:0xf bank_mask:0xf
	v_fmac_f32_dpp v11, v9, v77 row_shr:1 row_mask:0xf bank_mask:0xf
	v_fmac_f32_dpp v11, v9, v73 row_shr:2 row_mask:0xf bank_mask:0xf
	s_nop 0
	v_add_f32_e32 v46, v46, v11
	v_fma_f32 v11, v2, v82, v66
	v_mul_f32_dpp v13, v6, v74 row_shl:15 row_mask:0xf bank_mask:0xf bound_ctrl:0
	v_fmac_f32_dpp v13, v6, v70 row_shl:14 row_mask:0xf bank_mask:0xf
	v_fmac_f32_dpp v13, v2, v74 row_shr:1 row_mask:0xf bank_mask:0xf
	v_fmac_f32_dpp v13, v2, v70 row_shr:2 row_mask:0xf bank_mask:0xf
	v_fma_f32 v6, v3, v83, v67
	v_add_f32_e32 v11, v11, v13
	v_mul_f32_dpp v13, v7, v75 row_shl:15 row_mask:0xf bank_mask:0xf bound_ctrl:0
	v_fmac_f32_dpp v13, v7, v71 row_shl:14 row_mask:0xf bank_mask:0xf
	v_fmac_f32_dpp v13, v3, v75 row_shr:1 row_mask:0xf bank_mask:0xf
	v_fmac_f32_dpp v13, v3, v71 row_shr:2 row_mask:0xf bank_mask:0xf
	s_nop 0
	v_add_f32_e32 v6, v6, v13
	v_fma_f32 v13, v4, v84, v68
	v_mul_f32_dpp v7, v8, v76 row_shl:15 row_mask:0xf bank_mask:0xf bound_ctrl:0
	v_fmac_f32_dpp v7, v8, v72 row_shl:14 row_mask:0xf bank_mask:0xf
	v_fmac_f32_dpp v7, v4, v76 row_shr:1 row_mask:0xf bank_mask:0xf
	v_fmac_f32_dpp v7, v4, v72 row_shr:2 row_mask:0xf bank_mask:0xf
	s_nop 0
	v_add_f32_e32 v13, v13, v7
	v_mul_f32_dpp v7, v9, v77 row_shl:15 row_mask:0xf bank_mask:0xf bound_ctrl:0
	v_fmac_f32_dpp v7, v9, v73 row_shl:14 row_mask:0xf bank_mask:0xf
	v_fmac_f32_dpp v7, v5, v77 row_shr:1 row_mask:0xf bank_mask:0xf
	v_fmac_f32_dpp v7, v5, v73 row_shr:2 row_mask:0xf bank_mask:0xf
	v_fma_f32 v9, v5, v85, v69
	v_add_f32_e32 v9, v9, v7
	v_fma_f32 v8, v34, v82, v66
	v_mul_f32_dpp v7, v2, v74 row_shl:15 row_mask:0xf bank_mask:0xf bound_ctrl:0
	v_fmac_f32_dpp v7, v2, v70 row_shl:14 row_mask:0xf bank_mask:0xf
	v_fmac_f32_dpp v7, v34, v74 row_shr:1 row_mask:0xf bank_mask:0xf
	v_fmac_f32_dpp v7, v34, v70 row_shr:2 row_mask:0xf bank_mask:0xf
	v_fmac_f32_e32 v69, v37, v85
	v_add_f32_e32 v8, v8, v7
	v_fma_f32 v7, v35, v83, v67
	v_mul_f32_dpp v2, v3, v75 row_shl:15 row_mask:0xf bank_mask:0xf bound_ctrl:0
	v_fmac_f32_dpp v2, v3, v71 row_shl:14 row_mask:0xf bank_mask:0xf
	v_fmac_f32_dpp v2, v35, v75 row_shr:1 row_mask:0xf bank_mask:0xf
	v_fmac_f32_dpp v2, v35, v71 row_shr:2 row_mask:0xf bank_mask:0xf
	s_nop 0
	v_add_f32_e32 v7, v7, v2
	v_mul_f32_dpp v2, v4, v76 row_shl:15 row_mask:0xf bank_mask:0xf bound_ctrl:0
	v_fmac_f32_dpp v2, v4, v72 row_shl:14 row_mask:0xf bank_mask:0xf
	v_fmac_f32_dpp v2, v36, v76 row_shr:1 row_mask:0xf bank_mask:0xf
	v_fmac_f32_dpp v2, v36, v72 row_shr:2 row_mask:0xf bank_mask:0xf
	v_fma_f32 v4, v36, v84, v68
	v_add_f32_e32 v4, v4, v2
	v_mul_f32_dpp v2, v5, v77 row_shl:15 row_mask:0xf bank_mask:0xf bound_ctrl:0
	v_fmac_f32_dpp v2, v5, v73 row_shl:14 row_mask:0xf bank_mask:0xf
	v_fmac_f32_dpp v2, v37, v77 row_shr:1 row_mask:0xf bank_mask:0xf
	v_fmac_f32_dpp v2, v37, v73 row_shr:2 row_mask:0xf bank_mask:0xf
	s_nop 0
	v_add_f32_e32 v69, v69, v2
	v_mul_f32_e32 v2, 0xbfb8aa3b, v100
	v_mul_f32_e32 v3, 0xbfb8aa3b, v99
	v_exp_f32_e32 v2, v2
	v_exp_f32_e32 v3, v3
	v_mul_f32_e32 v34, 0xbfb8aa3b, v101
	v_mul_f32_e32 v35, 0xbfb8aa3b, v114
	v_exp_f32_e32 v34, v34
	v_exp_f32_e32 v35, v35
	v_add_f32_e32 v2, 1.0, v2
	v_add_f32_e32 v3, 1.0, v3
	v_rcp_f32_e32 v2, v2
	v_rcp_f32_e32 v3, v3
	v_add_f32_e32 v34, 1.0, v34
	v_add_f32_e32 v35, 1.0, v35
	v_rcp_f32_e32 v34, v34
	v_rcp_f32_e32 v35, v35
	v_mul_f32_e32 v2, v100, v2
	v_mul_f32_e32 v3, v99, v3
	v_mov_b32_e32 v5, v225
	v_mul_f32_e32 v2, v2, v52
	v_mul_f32_e32 v3, v3, v60
	v_mul_f32_e32 v34, v101, v34
	v_mul_f32_e32 v35, v114, v35
	v_mul_f32_e32 v34, v34, v61
	v_mul_f32_e32 v35, v35, v86
	v_cvt_pk_bf16_f32 v2, v2, v3
	v_cvt_pk_bf16_f32 v3, v34, v35
	s_and_saveexec_b64 s[8:9], s[36:37]
	s_cbranch_execz .LBB0_680
	v_mad_u64_u32 v[34:35], s[36:37], v5, s56, v[190:191]
	v_lshl_add_u32 v5, v34, 1, 8
	global_store_dwordx2 v5, v[2:3], s[90:91]
